# speedup vs baseline: 1.0002x; 1.0002x over previous
.LBB0_732:
	v_lshl_add_u32 v212, s72, 8, v222
	v_ashrrev_i32_e32 v213, 31, v212
	v_lshl_or_b32 v88, s33, 8, v224
	v_lshlrev_b64 v[90:91], 12, v[212:213]
	v_lshl_add_u64 v[90:91], s[30:31], 0, v[90:91]
	v_ashrrev_i32_e32 v89, 31, v88
	v_lshl_add_u64 v[210:211], v[88:89], 1, v[90:91]
	global_load_dwordx4 v[228:231], v[210:211], off
	global_load_dwordx4 v[186:189], v[210:211], off offset:256
	v_add_co_u32_e32 v88, vcc, 0x10000, v210
	v_readlane_b32 s8, v237, 51
	s_nop 0
	v_addc_co_u32_e32 v89, vcc, 0, v211, vcc
	v_readlane_b32 s11, v237, 54
	global_load_dwordx4 v[182:185], v[88:89], off
	global_load_dwordx4 v[178:181], v[88:89], off offset:256
	v_add_co_u32_e32 v88, vcc, s11, v210
	s_mov_b32 s8, 0x80000
	s_nop 0
	v_addc_co_u32_e32 v89, vcc, 0, v211, vcc
	global_load_dwordx4 v[174:177], v[88:89], off
	global_load_dwordx4 v[170:173], v[88:89], off offset:256
	v_add_co_u32_e32 v88, vcc, 0x30000, v210
	v_and_b32_e32 v227, 64, v214
	s_nop 0
	v_addc_co_u32_e32 v89, vcc, 0, v211, vcc
	global_load_dwordx4 v[166:169], v[88:89], off
	global_load_dwordx4 v[162:165], v[88:89], off offset:256
	v_add_co_u32_e32 v88, vcc, s8, v210
	s_mov_b32 s8, 0xb0000
	s_nop 0
	v_addc_co_u32_e32 v89, vcc, 0, v211, vcc
	global_load_dwordx4 v[154:157], v[88:89], off
	global_load_dwordx4 v[146:149], v[88:89], off offset:256
	v_add_co_u32_e32 v88, vcc, 0x90000, v210
	v_xor_b32_e32 v226, 16, v214
	s_nop 0
	v_addc_co_u32_e32 v89, vcc, 0, v211, vcc
	global_load_dwordx4 v[138:141], v[88:89], off
	global_load_dwordx4 v[130:133], v[88:89], off offset:256
	v_add_co_u32_e32 v88, vcc, 0xa0000, v210
	v_add_u32_e32 v227, 64, v227
	s_nop 0
	v_addc_co_u32_e32 v89, vcc, 0, v211, vcc
	global_load_dwordx4 v[116:119], v[88:89], off
	global_load_dwordx4 v[104:107], v[88:89], off offset:256
	v_add_co_u32_e32 v88, vcc, s8, v210
	v_xor_b32_e32 v232, 32, v214
	s_nop 0
	v_addc_co_u32_e32 v89, vcc, 0, v211, vcc
	global_load_dwordx4 v[96:99], v[88:89], off
	s_nop 0
	global_load_dwordx4 v[88:91], v[88:89], off offset:256
	v_cmp_lt_i32_e32 vcc, v226, v227
	v_readlane_b32 s9, v237, 52
	v_readlane_b32 s10, v237, 53
	v_cndmask_b32_e32 v226, v214, v226, vcc
	v_cmp_lt_i32_e32 vcc, v232, v227
	v_lshlrev_b32_e32 v226, 2, v226
	s_waitcnt vmcnt(0)
	v_and_b32_e32 v233, 0xffff0000, v228
	v_cndmask_b32_e32 v227, v214, v232, vcc
	v_lshlrev_b32_e32 v232, 16, v228
	v_lshlrev_b32_e32 v228, 16, v229
	v_and_b32_e32 v229, 0xffff0000, v229
	v_pk_add_f32 v[160:161], v[160:161], v[228:229]
	v_lshlrev_b32_e32 v228, 16, v230
	v_and_b32_e32 v229, 0xffff0000, v230
	v_pk_add_f32 v[228:229], v[150:151], v[228:229]
	v_lshlrev_b32_e32 v150, 16, v231
	v_and_b32_e32 v151, 0xffff0000, v231
	v_pk_add_f32 v[158:159], v[158:159], v[232:233]
	v_pk_add_f32 v[230:231], v[152:153], v[150:151]
	v_cvt_pk_bf16_f32 v150, v158, v159
	v_cvt_pk_bf16_f32 v151, v160, v161
	v_cvt_pk_bf16_f32 v152, v228, v229
	v_cvt_pk_bf16_f32 v153, v230, v231
	global_store_dwordx4 v[210:211], v[150:153], off sc1
	v_lshlrev_b32_e32 v227, 2, v227
	s_nop 0
	v_pk_mul_f32 v[150:151], v[158:159], v[158:159]
	v_pk_mul_f32 v[158:159], v[228:229], v[228:229]
	v_lshlrev_b32_e32 v228, 16, v186
	v_and_b32_e32 v229, 0xffff0000, v186
	v_lshlrev_b32_e32 v186, 16, v187
	v_and_b32_e32 v187, 0xffff0000, v187
	v_pk_add_f32 v[144:145], v[144:145], v[186:187]
	v_lshlrev_b32_e32 v186, 16, v188
	v_and_b32_e32 v187, 0xffff0000, v188
	v_pk_add_f32 v[186:187], v[134:135], v[186:187]
	v_lshlrev_b32_e32 v134, 16, v189
	v_and_b32_e32 v135, 0xffff0000, v189
	v_pk_add_f32 v[142:143], v[142:143], v[228:229]
	v_pk_add_f32 v[188:189], v[136:137], v[134:135]
	v_cvt_pk_bf16_f32 v134, v142, v143
	v_cvt_pk_bf16_f32 v135, v144, v145
	v_cvt_pk_bf16_f32 v136, v186, v187
	v_cvt_pk_bf16_f32 v137, v188, v189
	global_store_dwordx4 v[210:211], v[134:137], off offset:256 sc1
	v_pk_mul_f32 v[152:153], v[160:161], v[160:161]
	v_pk_mul_f32 v[160:161], v[230:231], v[230:231]
	v_pk_mul_f32 v[134:135], v[142:143], v[142:143]
	v_pk_mul_f32 v[136:137], v[144:145], v[144:145]
	v_add_f32_e32 v134, v134, v135
	v_add_f32_e32 v136, v136, v137
	v_pk_mul_f32 v[142:143], v[186:187], v[186:187]
	v_pk_mul_f32 v[144:145], v[188:189], v[188:189]
	v_add_f32_e32 v134, v134, v136
	v_add_f32_e32 v135, v160, v161
	v_add_f32_e32 v136, v158, v159
	v_add_f32_e32 v144, v144, v145
	v_add_f32_e32 v142, v142, v143
	v_add_f32_e32 v135, v136, v135
	v_add_f32_e32 v136, v152, v153
	v_add_f32_e32 v137, v150, v151
	v_add_f32_e32 v142, v142, v144
	v_add_f32_e32 v136, v137, v136
	v_add_f32_e32 v134, v134, v142
	v_add_f32_e32 v135, v136, v135
	v_add_f32_e32 v134, v135, v134
	ds_bpermute_b32 v135, v226, v134
	s_waitcnt lgkmcnt(0)
	v_add_f32_e32 v136, v134, v135
	ds_bpermute_b32 v137, v227, v136
	v_lshl_add_u64 v[134:135], v[212:213], 3, s[42:43]
	s_and_saveexec_b64 s[8:9], s[38:39]
	s_cbranch_execz .LBB0_734
	s_waitcnt lgkmcnt(0)
	v_add_f32_e32 v136, v136, v137
	v_mul_f32_e32 v136, 0x4b800000, v136
	v_trunc_f32_e32 v136, v136
	v_mul_f32_e32 v137, 0x2f800000, v136
	v_floor_f32_e32 v137, v137
	v_fmac_f32_e32 v136, 0xcf800000, v137
	v_cvt_u32_f32_e32 v136, v136
	v_cvt_u32_f32_e32 v137, v137
	global_atomic_add_x2 v[134:135], v[136:137], off
.LBB0_734:
	s_or_b64 exec, exec, s[8:9]
	v_lshlrev_b32_e32 v144, 16, v182
	v_and_b32_e32 v145, 0xffff0000, v182
	v_pk_add_f32 v[124:125], v[124:125], v[144:145]
	v_lshlrev_b32_e32 v144, 16, v183
	v_and_b32_e32 v145, 0xffff0000, v183
	v_pk_add_f32 v[126:127], v[126:127], v[144:145]
	v_lshlrev_b32_e32 v144, 16, v184
	v_and_b32_e32 v145, 0xffff0000, v184
	v_pk_add_f32 v[144:145], v[120:121], v[144:145]
	v_lshlrev_b32_e32 v120, 16, v185
	v_and_b32_e32 v121, 0xffff0000, v185
	s_mov_b64 s[8:9], 0x10000
	v_pk_add_f32 v[150:151], v[122:123], v[120:121]
	s_waitcnt lgkmcnt(0)
	v_lshl_add_u64 v[136:137], v[210:211], 0, s[8:9]
	v_cvt_pk_bf16_f32 v120, v124, v125
	v_cvt_pk_bf16_f32 v121, v126, v127
	v_cvt_pk_bf16_f32 v122, v144, v145
	v_cvt_pk_bf16_f32 v123, v150, v151
	global_store_dwordx4 v[136:137], v[120:123], off sc1
	v_lshlrev_b32_e32 v136, 16, v178
	v_and_b32_e32 v137, 0xffff0000, v178
	v_pk_add_f32 v[112:113], v[112:113], v[136:137]
	v_lshlrev_b32_e32 v136, 16, v179
	v_and_b32_e32 v137, 0xffff0000, v179
	v_pk_add_f32 v[114:115], v[114:115], v[136:137]
	v_lshlrev_b32_e32 v136, 16, v180
	v_and_b32_e32 v137, 0xffff0000, v180
	v_pk_add_f32 v[136:137], v[108:109], v[136:137]
	v_lshlrev_b32_e32 v108, 16, v181
	v_and_b32_e32 v109, 0xffff0000, v181
	s_mov_b64 s[8:9], 0x10100
	v_pk_mul_f32 v[120:121], v[124:125], v[124:125]
	v_pk_mul_f32 v[124:125], v[144:145], v[144:145]
	v_pk_add_f32 v[144:145], v[110:111], v[108:109]
	v_lshl_add_u64 v[142:143], v[210:211], 0, s[8:9]
	v_cvt_pk_bf16_f32 v108, v112, v113
	v_cvt_pk_bf16_f32 v109, v114, v115
	v_cvt_pk_bf16_f32 v110, v136, v137
	v_cvt_pk_bf16_f32 v111, v144, v145
	global_store_dwordx4 v[142:143], v[108:111], off sc1
	v_pk_mul_f32 v[122:123], v[126:127], v[126:127]
	v_pk_mul_f32 v[126:127], v[150:151], v[150:151]
	v_pk_mul_f32 v[108:109], v[112:113], v[112:113]
	v_pk_mul_f32 v[110:111], v[114:115], v[114:115]
	v_add_f32_e32 v108, v108, v109
	v_add_f32_e32 v110, v110, v111
	v_pk_mul_f32 v[112:113], v[136:137], v[136:137]
	v_pk_mul_f32 v[114:115], v[144:145], v[144:145]
	v_add_f32_e32 v108, v108, v110
	v_add_f32_e32 v109, v126, v127
	v_add_f32_e32 v110, v124, v125
	v_add_f32_e32 v114, v114, v115
	v_add_f32_e32 v112, v112, v113
	v_add_f32_e32 v109, v110, v109
	v_add_f32_e32 v110, v122, v123
	v_add_f32_e32 v111, v120, v121
	v_add_f32_e32 v112, v112, v114
	v_add_f32_e32 v110, v111, v110
	v_add_f32_e32 v108, v108, v112
	v_add_f32_e32 v109, v110, v109
	v_add_f32_e32 v108, v109, v108
	ds_bpermute_b32 v109, v226, v108
	s_waitcnt lgkmcnt(0)
	v_add_f32_e32 v108, v108, v109
	ds_bpermute_b32 v109, v227, v108
	s_and_saveexec_b64 s[8:9], s[38:39]
	s_cbranch_execz .LBB0_736
	s_waitcnt lgkmcnt(0)
	v_add_f32_e32 v108, v108, v109
	v_mul_f32_e32 v108, 0x4b800000, v108
	v_trunc_f32_e32 v108, v108
	v_mul_f32_e32 v109, 0x2f800000, v108
	v_floor_f32_e32 v109, v109
	v_fmac_f32_e32 v108, 0xcf800000, v109
	v_cvt_u32_f32_e32 v108, v108
	v_cvt_u32_f32_e32 v109, v109
	global_atomic_add_x2 v[134:135], v[108:109], off offset:128
.LBB0_736:
	s_or_b64 exec, exec, s[8:9]
	v_lshlrev_b32_e32 v112, 16, v174
	v_and_b32_e32 v113, 0xffff0000, v174
	v_pk_add_f32 v[100:101], v[100:101], v[112:113]
	v_lshlrev_b32_e32 v112, 16, v175
	v_and_b32_e32 v113, 0xffff0000, v175
	v_pk_add_f32 v[102:103], v[102:103], v[112:113]
	v_lshlrev_b32_e32 v112, 16, v176
	v_and_b32_e32 v113, 0xffff0000, v176
	v_pk_add_f32 v[112:113], v[92:93], v[112:113]
	v_lshlrev_b32_e32 v92, 16, v177
	v_and_b32_e32 v93, 0xffff0000, v177
	s_mov_b64 s[8:9], 0x20000
	v_pk_add_f32 v[114:115], v[94:95], v[92:93]
	s_waitcnt lgkmcnt(0)
	v_lshl_add_u64 v[108:109], v[210:211], 0, s[8:9]
	v_cvt_pk_bf16_f32 v92, v100, v101
	v_cvt_pk_bf16_f32 v93, v102, v103
	v_cvt_pk_bf16_f32 v94, v112, v113
	v_cvt_pk_bf16_f32 v95, v114, v115
	global_store_dwordx4 v[108:109], v[92:95], off sc1
	v_lshlrev_b32_e32 v108, 16, v170
	v_and_b32_e32 v109, 0xffff0000, v170
	v_pk_add_f32 v[84:85], v[84:85], v[108:109]
	v_lshlrev_b32_e32 v108, 16, v171
	v_and_b32_e32 v109, 0xffff0000, v171
	v_pk_add_f32 v[86:87], v[86:87], v[108:109]
	v_lshlrev_b32_e32 v108, 16, v172
	v_and_b32_e32 v109, 0xffff0000, v172
	v_pk_add_f32 v[108:109], v[80:81], v[108:109]
	v_lshlrev_b32_e32 v80, 16, v173
	v_and_b32_e32 v81, 0xffff0000, v173
	s_mov_b64 s[8:9], 0x20100
	v_pk_mul_f32 v[92:93], v[100:101], v[100:101]
	v_pk_mul_f32 v[100:101], v[112:113], v[112:113]
	v_pk_add_f32 v[112:113], v[82:83], v[80:81]
	v_lshl_add_u64 v[110:111], v[210:211], 0, s[8:9]
	v_cvt_pk_bf16_f32 v80, v84, v85
	v_cvt_pk_bf16_f32 v81, v86, v87
	v_cvt_pk_bf16_f32 v82, v108, v109
	v_cvt_pk_bf16_f32 v83, v112, v113
	global_store_dwordx4 v[110:111], v[80:83], off sc1
	v_pk_mul_f32 v[94:95], v[102:103], v[102:103]
	v_pk_mul_f32 v[102:103], v[114:115], v[114:115]
	v_pk_mul_f32 v[80:81], v[84:85], v[84:85]
	v_pk_mul_f32 v[82:83], v[86:87], v[86:87]
	v_add_f32_e32 v80, v80, v81
	v_add_f32_e32 v82, v82, v83
	v_pk_mul_f32 v[84:85], v[108:109], v[108:109]
	v_pk_mul_f32 v[86:87], v[112:113], v[112:113]
	v_add_f32_e32 v80, v80, v82
	v_add_f32_e32 v81, v102, v103
	v_add_f32_e32 v82, v100, v101
	v_add_f32_e32 v86, v86, v87
	v_add_f32_e32 v84, v84, v85
	v_add_f32_e32 v81, v82, v81
	v_add_f32_e32 v82, v94, v95
	v_add_f32_e32 v83, v92, v93
	v_add_f32_e32 v84, v84, v86
	v_add_f32_e32 v82, v83, v82
	v_add_f32_e32 v80, v80, v84
	v_add_f32_e32 v81, v82, v81
	v_add_f32_e32 v80, v81, v80
	ds_bpermute_b32 v81, v226, v80
	s_waitcnt lgkmcnt(0)
	v_add_f32_e32 v80, v80, v81
	ds_bpermute_b32 v81, v227, v80
	s_and_saveexec_b64 s[8:9], s[38:39]
	s_mov_b64 s[28:29], s[34:35]
	s_cbranch_execz .LBB0_738
	s_waitcnt lgkmcnt(0)
	v_add_f32_e32 v80, v80, v81
	v_mul_f32_e32 v80, 0x4b800000, v80
	v_trunc_f32_e32 v80, v80
	v_mul_f32_e32 v81, 0x2f800000, v80
	v_floor_f32_e32 v81, v81
	v_fmac_f32_e32 v80, 0xcf800000, v81
	v_cvt_u32_f32_e32 v80, v80
	v_cvt_u32_f32_e32 v81, v81
	global_atomic_add_x2 v[134:135], v[80:81], off offset:256
.LBB0_738:
	s_or_b64 exec, exec, s[8:9]
	v_lshlrev_b32_e32 v84, 16, v166
	v_and_b32_e32 v85, 0xffff0000, v166
	v_pk_add_f32 v[76:77], v[76:77], v[84:85]
	v_lshlrev_b32_e32 v84, 16, v167
	v_and_b32_e32 v85, 0xffff0000, v167
	v_pk_add_f32 v[78:79], v[78:79], v[84:85]
	v_lshlrev_b32_e32 v84, 16, v168
	v_and_b32_e32 v85, 0xffff0000, v168
	v_pk_add_f32 v[84:85], v[72:73], v[84:85]
	v_lshlrev_b32_e32 v72, 16, v169
	v_and_b32_e32 v73, 0xffff0000, v169
	s_mov_b64 s[8:9], 0x30000
	v_pk_add_f32 v[86:87], v[74:75], v[72:73]
	s_waitcnt lgkmcnt(0)
	v_lshl_add_u64 v[80:81], v[210:211], 0, s[8:9]
	v_cvt_pk_bf16_f32 v72, v76, v77
	v_cvt_pk_bf16_f32 v73, v78, v79
	v_cvt_pk_bf16_f32 v74, v84, v85
	v_cvt_pk_bf16_f32 v75, v86, v87
	global_store_dwordx4 v[80:81], v[72:75], off sc1
	v_lshlrev_b32_e32 v80, 16, v162
	v_and_b32_e32 v81, 0xffff0000, v162
	v_pk_add_f32 v[68:69], v[68:69], v[80:81]
	v_lshlrev_b32_e32 v80, 16, v163
	v_and_b32_e32 v81, 0xffff0000, v163
	v_pk_add_f32 v[70:71], v[70:71], v[80:81]
	v_lshlrev_b32_e32 v80, 16, v164
	v_and_b32_e32 v81, 0xffff0000, v164
	v_pk_add_f32 v[80:81], v[64:65], v[80:81]
	v_lshlrev_b32_e32 v64, 16, v165
	v_and_b32_e32 v65, 0xffff0000, v165
	s_mov_b64 s[8:9], 0x30100
	v_pk_mul_f32 v[72:73], v[76:77], v[76:77]
	v_pk_mul_f32 v[76:77], v[84:85], v[84:85]
	v_pk_add_f32 v[84:85], v[66:67], v[64:65]
	v_lshl_add_u64 v[82:83], v[210:211], 0, s[8:9]
	v_cvt_pk_bf16_f32 v64, v68, v69
	v_cvt_pk_bf16_f32 v65, v70, v71
	v_cvt_pk_bf16_f32 v66, v80, v81
	v_cvt_pk_bf16_f32 v67, v84, v85
	global_store_dwordx4 v[82:83], v[64:67], off sc1
	v_pk_mul_f32 v[74:75], v[78:79], v[78:79]
	v_pk_mul_f32 v[78:79], v[86:87], v[86:87]
	v_pk_mul_f32 v[64:65], v[68:69], v[68:69]
	v_pk_mul_f32 v[66:67], v[70:71], v[70:71]
	v_add_f32_e32 v64, v64, v65
	v_add_f32_e32 v66, v66, v67
	v_pk_mul_f32 v[68:69], v[80:81], v[80:81]
	v_pk_mul_f32 v[70:71], v[84:85], v[84:85]
	v_add_f32_e32 v64, v64, v66
	v_add_f32_e32 v65, v78, v79
	v_add_f32_e32 v66, v76, v77
	v_add_f32_e32 v70, v70, v71
	v_add_f32_e32 v68, v68, v69
	v_add_f32_e32 v65, v66, v65
	v_add_f32_e32 v66, v74, v75
	v_add_f32_e32 v67, v72, v73
	v_add_f32_e32 v68, v68, v70
	v_add_f32_e32 v66, v67, v66
	v_add_f32_e32 v64, v64, v68
	v_add_f32_e32 v65, v66, v65
	v_add_f32_e32 v64, v65, v64
	ds_bpermute_b32 v65, v226, v64
	s_waitcnt lgkmcnt(0)
	v_add_f32_e32 v64, v64, v65
	ds_bpermute_b32 v65, v227, v64
	s_and_saveexec_b64 s[8:9], s[38:39]
	s_cbranch_execz .LBB0_740
	s_waitcnt lgkmcnt(0)
	v_add_f32_e32 v64, v64, v65
	v_mul_f32_e32 v64, 0x4b800000, v64
	v_trunc_f32_e32 v64, v64
	v_mul_f32_e32 v65, 0x2f800000, v64
	v_floor_f32_e32 v65, v65
	v_fmac_f32_e32 v64, 0xcf800000, v65
	v_cvt_u32_f32_e32 v64, v64
	v_cvt_u32_f32_e32 v65, v65
	global_atomic_add_x2 v[134:135], v[64:65], off offset:384
.LBB0_740:
	s_or_b64 exec, exec, s[8:9]
	v_lshlrev_b32_e32 v68, 16, v154
	v_and_b32_e32 v69, 0xffff0000, v154
	v_pk_add_f32 v[60:61], v[60:61], v[68:69]
	v_lshlrev_b32_e32 v68, 16, v155
	v_and_b32_e32 v69, 0xffff0000, v155
	v_pk_add_f32 v[62:63], v[62:63], v[68:69]
	v_lshlrev_b32_e32 v68, 16, v156
	v_and_b32_e32 v69, 0xffff0000, v156
	v_pk_add_f32 v[68:69], v[56:57], v[68:69]
	v_lshlrev_b32_e32 v56, 16, v157
	v_and_b32_e32 v57, 0xffff0000, v157
	s_mov_b64 s[8:9], 0x80000
	v_pk_add_f32 v[70:71], v[58:59], v[56:57]
	s_waitcnt lgkmcnt(0)
	v_lshl_add_u64 v[64:65], v[210:211], 0, s[8:9]
	v_cvt_pk_bf16_f32 v56, v60, v61
	v_cvt_pk_bf16_f32 v57, v62, v63
	v_cvt_pk_bf16_f32 v58, v68, v69
	v_cvt_pk_bf16_f32 v59, v70, v71
	global_store_dwordx4 v[64:65], v[56:59], off sc1
	v_lshlrev_b32_e32 v64, 16, v146
	v_and_b32_e32 v65, 0xffff0000, v146
	v_pk_add_f32 v[52:53], v[52:53], v[64:65]
	v_lshlrev_b32_e32 v64, 16, v147
	v_and_b32_e32 v65, 0xffff0000, v147
	v_pk_add_f32 v[54:55], v[54:55], v[64:65]
	v_lshlrev_b32_e32 v64, 16, v148
	v_and_b32_e32 v65, 0xffff0000, v148
	v_pk_add_f32 v[64:65], v[48:49], v[64:65]
	v_lshlrev_b32_e32 v48, 16, v149
	v_and_b32_e32 v49, 0xffff0000, v149
	s_mov_b64 s[8:9], 0x80100
	v_pk_mul_f32 v[56:57], v[60:61], v[60:61]
	v_pk_mul_f32 v[60:61], v[68:69], v[68:69]
	v_pk_add_f32 v[68:69], v[50:51], v[48:49]
	v_lshl_add_u64 v[66:67], v[210:211], 0, s[8:9]
	v_cvt_pk_bf16_f32 v48, v52, v53
	v_cvt_pk_bf16_f32 v49, v54, v55
	v_cvt_pk_bf16_f32 v50, v64, v65
	v_cvt_pk_bf16_f32 v51, v68, v69
	global_store_dwordx4 v[66:67], v[48:51], off sc1
	v_pk_mul_f32 v[58:59], v[62:63], v[62:63]
	v_pk_mul_f32 v[62:63], v[70:71], v[70:71]
	v_pk_mul_f32 v[48:49], v[52:53], v[52:53]
	v_pk_mul_f32 v[50:51], v[54:55], v[54:55]
	v_add_f32_e32 v48, v48, v49
	v_add_f32_e32 v50, v50, v51
	v_pk_mul_f32 v[52:53], v[64:65], v[64:65]
	v_pk_mul_f32 v[54:55], v[68:69], v[68:69]
	v_add_f32_e32 v48, v48, v50
	v_add_f32_e32 v49, v62, v63
	v_add_f32_e32 v50, v60, v61
	v_add_f32_e32 v54, v54, v55
	v_add_f32_e32 v52, v52, v53
	v_add_f32_e32 v49, v50, v49
	v_add_f32_e32 v50, v58, v59
	v_add_f32_e32 v51, v56, v57
	v_add_f32_e32 v52, v52, v54
	v_add_f32_e32 v50, v51, v50
	v_add_f32_e32 v48, v48, v52
	v_add_f32_e32 v49, v50, v49
	v_add_f32_e32 v48, v49, v48
	ds_bpermute_b32 v49, v226, v48
	s_waitcnt lgkmcnt(0)
	v_add_f32_e32 v48, v48, v49
	ds_bpermute_b32 v49, v227, v48
	s_and_saveexec_b64 s[8:9], s[38:39]
	s_cbranch_execz .LBB0_742
	s_waitcnt lgkmcnt(0)
	v_add_f32_e32 v48, v48, v49
	v_mul_f32_e32 v48, 0x4b800000, v48
	v_trunc_f32_e32 v48, v48
	v_mul_f32_e32 v49, 0x2f800000, v48
	v_floor_f32_e32 v49, v49
	v_fmac_f32_e32 v48, 0xcf800000, v49
	v_cvt_u32_f32_e32 v48, v48
	v_cvt_u32_f32_e32 v49, v49
	global_atomic_add_x2 v[134:135], v[48:49], off offset:1024
.LBB0_742:
	s_or_b64 exec, exec, s[8:9]
	v_lshlrev_b32_e32 v52, 16, v138
	v_and_b32_e32 v53, 0xffff0000, v138
	v_pk_add_f32 v[44:45], v[44:45], v[52:53]
	v_lshlrev_b32_e32 v52, 16, v139
	v_and_b32_e32 v53, 0xffff0000, v139
	v_pk_add_f32 v[46:47], v[46:47], v[52:53]
	v_lshlrev_b32_e32 v52, 16, v140
	v_and_b32_e32 v53, 0xffff0000, v140
	v_pk_add_f32 v[52:53], v[40:41], v[52:53]
	v_lshlrev_b32_e32 v40, 16, v141
	v_and_b32_e32 v41, 0xffff0000, v141
	s_mov_b64 s[8:9], 0x90000
	v_pk_add_f32 v[54:55], v[42:43], v[40:41]
	s_waitcnt lgkmcnt(0)
	v_lshl_add_u64 v[48:49], v[210:211], 0, s[8:9]
	v_cvt_pk_bf16_f32 v40, v44, v45
	v_cvt_pk_bf16_f32 v41, v46, v47
	v_cvt_pk_bf16_f32 v42, v52, v53
	v_cvt_pk_bf16_f32 v43, v54, v55
	global_store_dwordx4 v[48:49], v[40:43], off sc1
	v_lshlrev_b32_e32 v48, 16, v130
	v_and_b32_e32 v49, 0xffff0000, v130
	v_pk_add_f32 v[36:37], v[36:37], v[48:49]
	v_lshlrev_b32_e32 v48, 16, v131
	v_and_b32_e32 v49, 0xffff0000, v131
	v_pk_add_f32 v[38:39], v[38:39], v[48:49]
	v_lshlrev_b32_e32 v48, 16, v132
	v_and_b32_e32 v49, 0xffff0000, v132
	v_pk_add_f32 v[48:49], v[32:33], v[48:49]
	v_lshlrev_b32_e32 v32, 16, v133
	v_and_b32_e32 v33, 0xffff0000, v133
	s_mov_b64 s[8:9], 0x90100
	v_pk_mul_f32 v[40:41], v[44:45], v[44:45]
	v_pk_mul_f32 v[44:45], v[52:53], v[52:53]
	v_pk_add_f32 v[52:53], v[34:35], v[32:33]
	v_lshl_add_u64 v[50:51], v[210:211], 0, s[8:9]
	v_cvt_pk_bf16_f32 v32, v36, v37
	v_cvt_pk_bf16_f32 v33, v38, v39
	v_cvt_pk_bf16_f32 v34, v48, v49
	v_cvt_pk_bf16_f32 v35, v52, v53
	global_store_dwordx4 v[50:51], v[32:35], off sc1
	v_pk_mul_f32 v[42:43], v[46:47], v[46:47]
	v_pk_mul_f32 v[46:47], v[54:55], v[54:55]
	v_pk_mul_f32 v[32:33], v[36:37], v[36:37]
	v_pk_mul_f32 v[34:35], v[38:39], v[38:39]
	v_add_f32_e32 v32, v32, v33
	v_add_f32_e32 v34, v34, v35
	v_pk_mul_f32 v[36:37], v[48:49], v[48:49]
	v_pk_mul_f32 v[38:39], v[52:53], v[52:53]
	v_add_f32_e32 v32, v32, v34
	v_add_f32_e32 v33, v46, v47
	v_add_f32_e32 v34, v44, v45
	v_add_f32_e32 v38, v38, v39
	v_add_f32_e32 v36, v36, v37
	v_add_f32_e32 v33, v34, v33
	v_add_f32_e32 v34, v42, v43
	v_add_f32_e32 v35, v40, v41
	v_add_f32_e32 v36, v36, v38
	v_add_f32_e32 v34, v35, v34
	v_add_f32_e32 v32, v32, v36
	v_add_f32_e32 v33, v34, v33
	v_add_f32_e32 v32, v33, v32
	ds_bpermute_b32 v33, v226, v32
	s_waitcnt lgkmcnt(0)
	v_add_f32_e32 v32, v32, v33
	ds_bpermute_b32 v33, v227, v32
	s_and_saveexec_b64 s[8:9], s[38:39]
	s_cbranch_execz .LBB0_744
	s_waitcnt lgkmcnt(0)
	v_add_f32_e32 v32, v32, v33
	v_mul_f32_e32 v32, 0x4b800000, v32
	v_trunc_f32_e32 v32, v32
	v_mul_f32_e32 v33, 0x2f800000, v32
	v_floor_f32_e32 v33, v33
	v_fmac_f32_e32 v32, 0xcf800000, v33
	v_cvt_u32_f32_e32 v32, v32
	v_cvt_u32_f32_e32 v33, v33
	global_atomic_add_x2 v[134:135], v[32:33], off offset:1152
.LBB0_744:
	s_or_b64 exec, exec, s[8:9]
	v_lshlrev_b32_e32 v36, 16, v116
	v_and_b32_e32 v37, 0xffff0000, v116
	v_pk_add_f32 v[28:29], v[28:29], v[36:37]
	v_lshlrev_b32_e32 v36, 16, v117
	v_and_b32_e32 v37, 0xffff0000, v117
	v_pk_add_f32 v[30:31], v[30:31], v[36:37]
	v_lshlrev_b32_e32 v36, 16, v118
	v_and_b32_e32 v37, 0xffff0000, v118
	v_pk_add_f32 v[36:37], v[24:25], v[36:37]
	v_lshlrev_b32_e32 v24, 16, v119
	v_and_b32_e32 v25, 0xffff0000, v119
	s_mov_b64 s[8:9], 0xa0000
	v_pk_add_f32 v[38:39], v[26:27], v[24:25]
	s_waitcnt lgkmcnt(0)
	v_lshl_add_u64 v[32:33], v[210:211], 0, s[8:9]
	v_cvt_pk_bf16_f32 v24, v28, v29
	v_cvt_pk_bf16_f32 v25, v30, v31
	v_cvt_pk_bf16_f32 v26, v36, v37
	v_cvt_pk_bf16_f32 v27, v38, v39
	global_store_dwordx4 v[32:33], v[24:27], off sc1
	v_lshlrev_b32_e32 v32, 16, v104
	v_and_b32_e32 v33, 0xffff0000, v104
	v_pk_add_f32 v[20:21], v[20:21], v[32:33]
	v_lshlrev_b32_e32 v32, 16, v105
	v_and_b32_e32 v33, 0xffff0000, v105
	v_pk_add_f32 v[22:23], v[22:23], v[32:33]
	v_lshlrev_b32_e32 v32, 16, v106
	v_and_b32_e32 v33, 0xffff0000, v106
	v_pk_add_f32 v[32:33], v[16:17], v[32:33]
	v_lshlrev_b32_e32 v16, 16, v107
	v_and_b32_e32 v17, 0xffff0000, v107
	s_mov_b64 s[8:9], 0xa0100
	v_pk_mul_f32 v[24:25], v[28:29], v[28:29]
	v_pk_mul_f32 v[28:29], v[36:37], v[36:37]
	v_pk_add_f32 v[36:37], v[18:19], v[16:17]
	v_lshl_add_u64 v[34:35], v[210:211], 0, s[8:9]
	v_cvt_pk_bf16_f32 v16, v20, v21
	v_cvt_pk_bf16_f32 v17, v22, v23
	v_cvt_pk_bf16_f32 v18, v32, v33
	v_cvt_pk_bf16_f32 v19, v36, v37
	global_store_dwordx4 v[34:35], v[16:19], off sc1
	v_pk_mul_f32 v[26:27], v[30:31], v[30:31]
	v_pk_mul_f32 v[30:31], v[38:39], v[38:39]
	v_pk_mul_f32 v[16:17], v[20:21], v[20:21]
	v_pk_mul_f32 v[18:19], v[22:23], v[22:23]
	v_add_f32_e32 v16, v16, v17
	v_add_f32_e32 v18, v18, v19
	v_pk_mul_f32 v[20:21], v[32:33], v[32:33]
	v_pk_mul_f32 v[22:23], v[36:37], v[36:37]
	v_add_f32_e32 v16, v16, v18
	v_add_f32_e32 v17, v30, v31
	v_add_f32_e32 v18, v28, v29
	v_add_f32_e32 v22, v22, v23
	v_add_f32_e32 v20, v20, v21
	v_add_f32_e32 v17, v18, v17
	v_add_f32_e32 v18, v26, v27
	v_add_f32_e32 v19, v24, v25
	v_add_f32_e32 v20, v20, v22
	v_add_f32_e32 v18, v19, v18
	v_add_f32_e32 v16, v16, v20
	v_add_f32_e32 v17, v18, v17
	v_add_f32_e32 v16, v17, v16
	ds_bpermute_b32 v17, v226, v16
	s_waitcnt lgkmcnt(0)
	v_add_f32_e32 v16, v16, v17
	ds_bpermute_b32 v17, v227, v16
	s_and_saveexec_b64 s[8:9], s[38:39]
	s_cbranch_execz .LBB0_746
	s_waitcnt lgkmcnt(0)
	v_add_f32_e32 v16, v16, v17
	v_mul_f32_e32 v16, 0x4b800000, v16
	v_trunc_f32_e32 v16, v16
	v_mul_f32_e32 v17, 0x2f800000, v16
	v_floor_f32_e32 v17, v17
	v_fmac_f32_e32 v16, 0xcf800000, v17
	v_cvt_u32_f32_e32 v16, v16
	v_cvt_u32_f32_e32 v17, v17
	global_atomic_add_x2 v[134:135], v[16:17], off offset:1280
.LBB0_746:
	s_or_b64 exec, exec, s[8:9]
	v_lshlrev_b32_e32 v20, 16, v96
	v_and_b32_e32 v21, 0xffff0000, v96
	v_pk_add_f32 v[12:13], v[12:13], v[20:21]
	v_lshlrev_b32_e32 v20, 16, v97
	v_and_b32_e32 v21, 0xffff0000, v97
	v_pk_add_f32 v[14:15], v[14:15], v[20:21]
	v_lshlrev_b32_e32 v20, 16, v98
	v_and_b32_e32 v21, 0xffff0000, v98
	v_pk_add_f32 v[20:21], v[8:9], v[20:21]
	v_lshlrev_b32_e32 v8, 16, v99
	v_and_b32_e32 v9, 0xffff0000, v99
	s_mov_b64 s[8:9], 0xb0000
	v_pk_add_f32 v[22:23], v[10:11], v[8:9]
	s_waitcnt lgkmcnt(0)
	v_lshl_add_u64 v[16:17], v[210:211], 0, s[8:9]
	v_cvt_pk_bf16_f32 v8, v12, v13
	v_cvt_pk_bf16_f32 v9, v14, v15
	v_cvt_pk_bf16_f32 v10, v20, v21
	v_cvt_pk_bf16_f32 v11, v22, v23
	global_store_dwordx4 v[16:17], v[8:11], off sc1
	v_lshlrev_b32_e32 v16, 16, v88
	v_and_b32_e32 v17, 0xffff0000, v88
	v_pk_add_f32 v[4:5], v[4:5], v[16:17]
	v_lshlrev_b32_e32 v16, 16, v89
	v_and_b32_e32 v17, 0xffff0000, v89
	v_pk_add_f32 v[6:7], v[6:7], v[16:17]
	v_lshlrev_b32_e32 v16, 16, v90
	v_and_b32_e32 v17, 0xffff0000, v90
	v_pk_add_f32 v[16:17], v[0:1], v[16:17]
	v_lshlrev_b32_e32 v0, 16, v91
	v_and_b32_e32 v1, 0xffff0000, v91
	s_mov_b64 s[8:9], 0xb0100
	v_pk_mul_f32 v[8:9], v[12:13], v[12:13]
	v_pk_mul_f32 v[12:13], v[20:21], v[20:21]
	v_pk_add_f32 v[20:21], v[2:3], v[0:1]
	v_lshl_add_u64 v[18:19], v[210:211], 0, s[8:9]
	v_cvt_pk_bf16_f32 v0, v4, v5
	v_cvt_pk_bf16_f32 v1, v6, v7
	v_cvt_pk_bf16_f32 v2, v16, v17
	v_cvt_pk_bf16_f32 v3, v20, v21
	global_store_dwordx4 v[18:19], v[0:3], off sc1
	v_pk_mul_f32 v[10:11], v[14:15], v[14:15]
	v_pk_mul_f32 v[14:15], v[22:23], v[22:23]
	v_pk_mul_f32 v[0:1], v[4:5], v[4:5]
	v_pk_mul_f32 v[2:3], v[6:7], v[6:7]
	v_add_f32_e32 v0, v0, v1
	v_add_f32_e32 v2, v2, v3
	v_pk_mul_f32 v[4:5], v[16:17], v[16:17]
	v_pk_mul_f32 v[6:7], v[20:21], v[20:21]
	v_add_f32_e32 v0, v0, v2
	v_add_f32_e32 v1, v14, v15
	v_add_f32_e32 v2, v12, v13
	v_add_f32_e32 v6, v6, v7
	v_add_f32_e32 v4, v4, v5
	v_add_f32_e32 v1, v2, v1
	v_add_f32_e32 v2, v10, v11
	v_add_f32_e32 v3, v8, v9
	v_add_f32_e32 v4, v4, v6
	v_add_f32_e32 v2, v3, v2
	v_add_f32_e32 v0, v0, v4
	v_add_f32_e32 v1, v2, v1
	v_add_f32_e32 v0, v1, v0
	ds_bpermute_b32 v1, v226, v0
	s_waitcnt lgkmcnt(0)
	v_add_f32_e32 v0, v0, v1
	ds_bpermute_b32 v1, v227, v0
	s_and_saveexec_b64 s[8:9], s[38:39]
	s_cbranch_execz .LBB0_748
	s_waitcnt lgkmcnt(0)
	v_add_f32_e32 v0, v0, v1
	v_mul_f32_e32 v0, 0x4b800000, v0
	v_trunc_f32_e32 v0, v0
	v_mul_f32_e32 v1, 0x2f800000, v0
	v_floor_f32_e32 v1, v1
	v_fmac_f32_e32 v0, 0xcf800000, v1
	v_cvt_u32_f32_e32 v0, v0
	v_cvt_u32_f32_e32 v1, v1
	global_atomic_add_x2 v[134:135], v[0:1], off offset:1408

.LBB0_1041:
	v_lshl_add_u32 v212, s72, 8, v222
	v_ashrrev_i32_e32 v213, 31, v212
	v_lshl_or_b32 v88, s33, 8, v224
	v_lshlrev_b64 v[90:91], 12, v[212:213]
	v_lshl_add_u64 v[90:91], s[30:31], 0, v[90:91]
	v_ashrrev_i32_e32 v89, 31, v88
	v_lshl_add_u64 v[210:211], v[88:89], 1, v[90:91]
	global_load_dwordx4 v[228:231], v[210:211], off
	global_load_dwordx4 v[186:189], v[210:211], off offset:256
	v_add_co_u32_e32 v88, vcc, 0x10000, v210
	v_readlane_b32 s8, v237, 51
	s_nop 0
	v_addc_co_u32_e32 v89, vcc, 0, v211, vcc
	v_readlane_b32 s11, v237, 54
	global_load_dwordx4 v[182:185], v[88:89], off
	global_load_dwordx4 v[178:181], v[88:89], off offset:256
	v_add_co_u32_e32 v88, vcc, s11, v210
	s_mov_b32 s8, 0x80000
	s_nop 0
	v_addc_co_u32_e32 v89, vcc, 0, v211, vcc
	global_load_dwordx4 v[174:177], v[88:89], off
	global_load_dwordx4 v[170:173], v[88:89], off offset:256
	v_add_co_u32_e32 v88, vcc, 0x30000, v210
	v_and_b32_e32 v227, 64, v214
	s_nop 0
	v_addc_co_u32_e32 v89, vcc, 0, v211, vcc
	global_load_dwordx4 v[166:169], v[88:89], off
	global_load_dwordx4 v[162:165], v[88:89], off offset:256
	v_add_co_u32_e32 v88, vcc, s8, v210
	s_mov_b32 s8, 0xb0000
	s_nop 0
	v_addc_co_u32_e32 v89, vcc, 0, v211, vcc
	global_load_dwordx4 v[154:157], v[88:89], off
	global_load_dwordx4 v[146:149], v[88:89], off offset:256
	v_add_co_u32_e32 v88, vcc, 0x90000, v210
	v_xor_b32_e32 v226, 16, v214
	s_nop 0
	v_addc_co_u32_e32 v89, vcc, 0, v211, vcc
	global_load_dwordx4 v[138:141], v[88:89], off
	global_load_dwordx4 v[130:133], v[88:89], off offset:256
	v_add_co_u32_e32 v88, vcc, 0xa0000, v210
	v_add_u32_e32 v227, 64, v227
	s_nop 0
	v_addc_co_u32_e32 v89, vcc, 0, v211, vcc
	global_load_dwordx4 v[116:119], v[88:89], off
	global_load_dwordx4 v[104:107], v[88:89], off offset:256
	v_add_co_u32_e32 v88, vcc, s8, v210
	v_xor_b32_e32 v232, 32, v214
	s_nop 0
	v_addc_co_u32_e32 v89, vcc, 0, v211, vcc
	global_load_dwordx4 v[96:99], v[88:89], off
	s_nop 0
	global_load_dwordx4 v[88:91], v[88:89], off offset:256
	v_cmp_lt_i32_e32 vcc, v226, v227
	v_readlane_b32 s9, v237, 52
	v_readlane_b32 s10, v237, 53
	v_cndmask_b32_e32 v226, v214, v226, vcc
	v_cmp_lt_i32_e32 vcc, v232, v227
	v_lshlrev_b32_e32 v226, 2, v226
	s_waitcnt vmcnt(0)
	v_and_b32_e32 v233, 0xffff0000, v228
	v_cndmask_b32_e32 v227, v214, v232, vcc
	v_lshlrev_b32_e32 v232, 16, v228
	v_lshlrev_b32_e32 v228, 16, v229
	v_and_b32_e32 v229, 0xffff0000, v229
	v_pk_add_f32 v[160:161], v[160:161], v[228:229]
	v_lshlrev_b32_e32 v228, 16, v230
	v_and_b32_e32 v229, 0xffff0000, v230
	v_pk_add_f32 v[228:229], v[150:151], v[228:229]
	v_lshlrev_b32_e32 v150, 16, v231
	v_and_b32_e32 v151, 0xffff0000, v231
	v_pk_add_f32 v[158:159], v[158:159], v[232:233]
	v_pk_add_f32 v[230:231], v[152:153], v[150:151]
	v_cvt_pk_bf16_f32 v150, v158, v159
	v_cvt_pk_bf16_f32 v151, v160, v161
	v_cvt_pk_bf16_f32 v152, v228, v229
	v_cvt_pk_bf16_f32 v153, v230, v231
	global_store_dwordx4 v[210:211], v[150:153], off sc1
	v_lshlrev_b32_e32 v227, 2, v227
	s_nop 0
	v_pk_mul_f32 v[150:151], v[158:159], v[158:159]
	v_pk_mul_f32 v[158:159], v[228:229], v[228:229]
	v_lshlrev_b32_e32 v228, 16, v186
	v_and_b32_e32 v229, 0xffff0000, v186
	v_lshlrev_b32_e32 v186, 16, v187
	v_and_b32_e32 v187, 0xffff0000, v187
	v_pk_add_f32 v[144:145], v[144:145], v[186:187]
	v_lshlrev_b32_e32 v186, 16, v188
	v_and_b32_e32 v187, 0xffff0000, v188
	v_pk_add_f32 v[186:187], v[134:135], v[186:187]
	v_lshlrev_b32_e32 v134, 16, v189
	v_and_b32_e32 v135, 0xffff0000, v189
	v_pk_add_f32 v[142:143], v[142:143], v[228:229]
	v_pk_add_f32 v[188:189], v[136:137], v[134:135]
	v_cvt_pk_bf16_f32 v134, v142, v143
	v_cvt_pk_bf16_f32 v135, v144, v145
	v_cvt_pk_bf16_f32 v136, v186, v187
	v_cvt_pk_bf16_f32 v137, v188, v189
	global_store_dwordx4 v[210:211], v[134:137], off offset:256 sc1
	v_pk_mul_f32 v[152:153], v[160:161], v[160:161]
	v_pk_mul_f32 v[160:161], v[230:231], v[230:231]
	v_pk_mul_f32 v[134:135], v[142:143], v[142:143]
	v_pk_mul_f32 v[136:137], v[144:145], v[144:145]
	v_add_f32_e32 v134, v134, v135
	v_add_f32_e32 v136, v136, v137
	v_pk_mul_f32 v[142:143], v[186:187], v[186:187]
	v_pk_mul_f32 v[144:145], v[188:189], v[188:189]
	v_add_f32_e32 v134, v134, v136
	v_add_f32_e32 v135, v160, v161
	v_add_f32_e32 v136, v158, v159
	v_add_f32_e32 v144, v144, v145
	v_add_f32_e32 v142, v142, v143
	v_add_f32_e32 v135, v136, v135
	v_add_f32_e32 v136, v152, v153
	v_add_f32_e32 v137, v150, v151
	v_add_f32_e32 v142, v142, v144
	v_add_f32_e32 v136, v137, v136
	v_add_f32_e32 v134, v134, v142
	v_add_f32_e32 v135, v136, v135
	v_add_f32_e32 v134, v135, v134
	ds_bpermute_b32 v135, v226, v134
	s_waitcnt lgkmcnt(0)
	v_add_f32_e32 v136, v134, v135
	ds_bpermute_b32 v137, v227, v136
	v_lshl_add_u64 v[134:135], v[212:213], 3, s[38:39]
	s_and_saveexec_b64 s[8:9], s[40:41]
	s_cbranch_execz .LBB0_1043
	s_waitcnt lgkmcnt(0)
	v_add_f32_e32 v136, v136, v137
	v_mul_f32_e32 v136, 0x4b800000, v136
	v_trunc_f32_e32 v136, v136
	v_mul_f32_e32 v137, 0x2f800000, v136
	v_floor_f32_e32 v137, v137
	v_fmac_f32_e32 v136, 0xcf800000, v137
	v_cvt_u32_f32_e32 v136, v136
	v_cvt_u32_f32_e32 v137, v137
	global_atomic_add_x2 v[134:135], v[136:137], off
.LBB0_1043:
	s_or_b64 exec, exec, s[8:9]
	v_lshlrev_b32_e32 v144, 16, v182
	v_and_b32_e32 v145, 0xffff0000, v182
	v_pk_add_f32 v[124:125], v[124:125], v[144:145]
	v_lshlrev_b32_e32 v144, 16, v183
	v_and_b32_e32 v145, 0xffff0000, v183
	v_pk_add_f32 v[126:127], v[126:127], v[144:145]
	v_lshlrev_b32_e32 v144, 16, v184
	v_and_b32_e32 v145, 0xffff0000, v184
	v_pk_add_f32 v[144:145], v[120:121], v[144:145]
	v_lshlrev_b32_e32 v120, 16, v185
	v_and_b32_e32 v121, 0xffff0000, v185
	s_mov_b64 s[8:9], 0x10000
	v_pk_add_f32 v[150:151], v[122:123], v[120:121]
	s_waitcnt lgkmcnt(0)
	v_lshl_add_u64 v[136:137], v[210:211], 0, s[8:9]
	v_cvt_pk_bf16_f32 v120, v124, v125
	v_cvt_pk_bf16_f32 v121, v126, v127
	v_cvt_pk_bf16_f32 v122, v144, v145
	v_cvt_pk_bf16_f32 v123, v150, v151
	global_store_dwordx4 v[136:137], v[120:123], off sc1
	v_lshlrev_b32_e32 v136, 16, v178
	v_and_b32_e32 v137, 0xffff0000, v178
	v_pk_add_f32 v[112:113], v[112:113], v[136:137]
	v_lshlrev_b32_e32 v136, 16, v179
	v_and_b32_e32 v137, 0xffff0000, v179
	v_pk_add_f32 v[114:115], v[114:115], v[136:137]
	v_lshlrev_b32_e32 v136, 16, v180
	v_and_b32_e32 v137, 0xffff0000, v180
	v_pk_add_f32 v[136:137], v[108:109], v[136:137]
	v_lshlrev_b32_e32 v108, 16, v181
	v_and_b32_e32 v109, 0xffff0000, v181
	s_mov_b64 s[8:9], 0x10100
	v_pk_mul_f32 v[120:121], v[124:125], v[124:125]
	v_pk_mul_f32 v[124:125], v[144:145], v[144:145]
	v_pk_add_f32 v[144:145], v[110:111], v[108:109]
	v_lshl_add_u64 v[142:143], v[210:211], 0, s[8:9]
	v_cvt_pk_bf16_f32 v108, v112, v113
	v_cvt_pk_bf16_f32 v109, v114, v115
	v_cvt_pk_bf16_f32 v110, v136, v137
	v_cvt_pk_bf16_f32 v111, v144, v145
	global_store_dwordx4 v[142:143], v[108:111], off sc1
	v_pk_mul_f32 v[122:123], v[126:127], v[126:127]
	v_pk_mul_f32 v[126:127], v[150:151], v[150:151]
	v_pk_mul_f32 v[108:109], v[112:113], v[112:113]
	v_pk_mul_f32 v[110:111], v[114:115], v[114:115]
	v_add_f32_e32 v108, v108, v109
	v_add_f32_e32 v110, v110, v111
	v_pk_mul_f32 v[112:113], v[136:137], v[136:137]
	v_pk_mul_f32 v[114:115], v[144:145], v[144:145]
	v_add_f32_e32 v108, v108, v110
	v_add_f32_e32 v109, v126, v127
	v_add_f32_e32 v110, v124, v125
	v_add_f32_e32 v114, v114, v115
	v_add_f32_e32 v112, v112, v113
	v_add_f32_e32 v109, v110, v109
	v_add_f32_e32 v110, v122, v123
	v_add_f32_e32 v111, v120, v121
	v_add_f32_e32 v112, v112, v114
	v_add_f32_e32 v110, v111, v110
	v_add_f32_e32 v108, v108, v112
	v_add_f32_e32 v109, v110, v109
	v_add_f32_e32 v108, v109, v108
	ds_bpermute_b32 v109, v226, v108
	s_waitcnt lgkmcnt(0)
	v_add_f32_e32 v108, v108, v109
	ds_bpermute_b32 v109, v227, v108
	s_and_saveexec_b64 s[8:9], s[40:41]
	s_cbranch_execz .LBB0_1045
	s_waitcnt lgkmcnt(0)
	v_add_f32_e32 v108, v108, v109
	v_mul_f32_e32 v108, 0x4b800000, v108
	v_trunc_f32_e32 v108, v108
	v_mul_f32_e32 v109, 0x2f800000, v108
	v_floor_f32_e32 v109, v109
	v_fmac_f32_e32 v108, 0xcf800000, v109
	v_cvt_u32_f32_e32 v108, v108
	v_cvt_u32_f32_e32 v109, v109
	global_atomic_add_x2 v[134:135], v[108:109], off offset:128
.LBB0_1045:
	s_or_b64 exec, exec, s[8:9]
	v_lshlrev_b32_e32 v112, 16, v174
	v_and_b32_e32 v113, 0xffff0000, v174
	v_pk_add_f32 v[100:101], v[100:101], v[112:113]
	v_lshlrev_b32_e32 v112, 16, v175
	v_and_b32_e32 v113, 0xffff0000, v175
	v_pk_add_f32 v[102:103], v[102:103], v[112:113]
	v_lshlrev_b32_e32 v112, 16, v176
	v_and_b32_e32 v113, 0xffff0000, v176
	v_pk_add_f32 v[112:113], v[92:93], v[112:113]
	v_lshlrev_b32_e32 v92, 16, v177
	v_and_b32_e32 v93, 0xffff0000, v177
	s_mov_b64 s[8:9], 0x20000
	v_pk_add_f32 v[114:115], v[94:95], v[92:93]
	s_waitcnt lgkmcnt(0)
	v_lshl_add_u64 v[108:109], v[210:211], 0, s[8:9]
	v_cvt_pk_bf16_f32 v92, v100, v101
	v_cvt_pk_bf16_f32 v93, v102, v103
	v_cvt_pk_bf16_f32 v94, v112, v113
	v_cvt_pk_bf16_f32 v95, v114, v115
	global_store_dwordx4 v[108:109], v[92:95], off sc1
	v_lshlrev_b32_e32 v108, 16, v170
	v_and_b32_e32 v109, 0xffff0000, v170
	v_pk_add_f32 v[84:85], v[84:85], v[108:109]
	v_lshlrev_b32_e32 v108, 16, v171
	v_and_b32_e32 v109, 0xffff0000, v171
	v_pk_add_f32 v[86:87], v[86:87], v[108:109]
	v_lshlrev_b32_e32 v108, 16, v172
	v_and_b32_e32 v109, 0xffff0000, v172
	v_pk_add_f32 v[108:109], v[80:81], v[108:109]
	v_lshlrev_b32_e32 v80, 16, v173
	v_and_b32_e32 v81, 0xffff0000, v173
	s_mov_b64 s[8:9], 0x20100
	v_pk_mul_f32 v[92:93], v[100:101], v[100:101]
	v_pk_mul_f32 v[100:101], v[112:113], v[112:113]
	v_pk_add_f32 v[112:113], v[82:83], v[80:81]
	v_lshl_add_u64 v[110:111], v[210:211], 0, s[8:9]
	v_cvt_pk_bf16_f32 v80, v84, v85
	v_cvt_pk_bf16_f32 v81, v86, v87
	v_cvt_pk_bf16_f32 v82, v108, v109
	v_cvt_pk_bf16_f32 v83, v112, v113
	global_store_dwordx4 v[110:111], v[80:83], off sc1
	v_pk_mul_f32 v[94:95], v[102:103], v[102:103]
	v_pk_mul_f32 v[102:103], v[114:115], v[114:115]
	v_pk_mul_f32 v[80:81], v[84:85], v[84:85]
	v_pk_mul_f32 v[82:83], v[86:87], v[86:87]
	v_add_f32_e32 v80, v80, v81
	v_add_f32_e32 v82, v82, v83
	v_pk_mul_f32 v[84:85], v[108:109], v[108:109]
	v_pk_mul_f32 v[86:87], v[112:113], v[112:113]
	v_add_f32_e32 v80, v80, v82
	v_add_f32_e32 v81, v102, v103
	v_add_f32_e32 v82, v100, v101
	v_add_f32_e32 v86, v86, v87
	v_add_f32_e32 v84, v84, v85
	v_add_f32_e32 v81, v82, v81
	v_add_f32_e32 v82, v94, v95
	v_add_f32_e32 v83, v92, v93
	v_add_f32_e32 v84, v84, v86
	v_add_f32_e32 v82, v83, v82
	v_add_f32_e32 v80, v80, v84
	v_add_f32_e32 v81, v82, v81
	v_add_f32_e32 v80, v81, v80
	ds_bpermute_b32 v81, v226, v80
	s_waitcnt lgkmcnt(0)
	v_add_f32_e32 v80, v80, v81
	ds_bpermute_b32 v81, v227, v80
	s_and_saveexec_b64 s[8:9], s[40:41]
	s_mov_b64 s[28:29], s[34:35]
	s_cbranch_execz .LBB0_1047
	s_waitcnt lgkmcnt(0)
	v_add_f32_e32 v80, v80, v81
	v_mul_f32_e32 v80, 0x4b800000, v80
	v_trunc_f32_e32 v80, v80
	v_mul_f32_e32 v81, 0x2f800000, v80
	v_floor_f32_e32 v81, v81
	v_fmac_f32_e32 v80, 0xcf800000, v81
	v_cvt_u32_f32_e32 v80, v80
	v_cvt_u32_f32_e32 v81, v81
	global_atomic_add_x2 v[134:135], v[80:81], off offset:256
.LBB0_1047:
	s_or_b64 exec, exec, s[8:9]
	v_lshlrev_b32_e32 v84, 16, v166
	v_and_b32_e32 v85, 0xffff0000, v166
	v_pk_add_f32 v[76:77], v[76:77], v[84:85]
	v_lshlrev_b32_e32 v84, 16, v167
	v_and_b32_e32 v85, 0xffff0000, v167
	v_pk_add_f32 v[78:79], v[78:79], v[84:85]
	v_lshlrev_b32_e32 v84, 16, v168
	v_and_b32_e32 v85, 0xffff0000, v168
	v_pk_add_f32 v[84:85], v[72:73], v[84:85]
	v_lshlrev_b32_e32 v72, 16, v169
	v_and_b32_e32 v73, 0xffff0000, v169
	s_mov_b64 s[8:9], 0x30000
	v_pk_add_f32 v[86:87], v[74:75], v[72:73]
	s_waitcnt lgkmcnt(0)
	v_lshl_add_u64 v[80:81], v[210:211], 0, s[8:9]
	v_cvt_pk_bf16_f32 v72, v76, v77
	v_cvt_pk_bf16_f32 v73, v78, v79
	v_cvt_pk_bf16_f32 v74, v84, v85
	v_cvt_pk_bf16_f32 v75, v86, v87
	global_store_dwordx4 v[80:81], v[72:75], off sc1
	v_lshlrev_b32_e32 v80, 16, v162
	v_and_b32_e32 v81, 0xffff0000, v162
	v_pk_add_f32 v[68:69], v[68:69], v[80:81]
	v_lshlrev_b32_e32 v80, 16, v163
	v_and_b32_e32 v81, 0xffff0000, v163
	v_pk_add_f32 v[70:71], v[70:71], v[80:81]
	v_lshlrev_b32_e32 v80, 16, v164
	v_and_b32_e32 v81, 0xffff0000, v164
	v_pk_add_f32 v[80:81], v[64:65], v[80:81]
	v_lshlrev_b32_e32 v64, 16, v165
	v_and_b32_e32 v65, 0xffff0000, v165
	s_mov_b64 s[8:9], 0x30100
	v_pk_mul_f32 v[72:73], v[76:77], v[76:77]
	v_pk_mul_f32 v[76:77], v[84:85], v[84:85]
	v_pk_add_f32 v[84:85], v[66:67], v[64:65]
	v_lshl_add_u64 v[82:83], v[210:211], 0, s[8:9]
	v_cvt_pk_bf16_f32 v64, v68, v69
	v_cvt_pk_bf16_f32 v65, v70, v71
	v_cvt_pk_bf16_f32 v66, v80, v81
	v_cvt_pk_bf16_f32 v67, v84, v85
	global_store_dwordx4 v[82:83], v[64:67], off sc1
	v_pk_mul_f32 v[74:75], v[78:79], v[78:79]
	v_pk_mul_f32 v[78:79], v[86:87], v[86:87]
	v_pk_mul_f32 v[64:65], v[68:69], v[68:69]
	v_pk_mul_f32 v[66:67], v[70:71], v[70:71]
	v_add_f32_e32 v64, v64, v65
	v_add_f32_e32 v66, v66, v67
	v_pk_mul_f32 v[68:69], v[80:81], v[80:81]
	v_pk_mul_f32 v[70:71], v[84:85], v[84:85]
	v_add_f32_e32 v64, v64, v66
	v_add_f32_e32 v65, v78, v79
	v_add_f32_e32 v66, v76, v77
	v_add_f32_e32 v70, v70, v71
	v_add_f32_e32 v68, v68, v69
	v_add_f32_e32 v65, v66, v65
	v_add_f32_e32 v66, v74, v75
	v_add_f32_e32 v67, v72, v73
	v_add_f32_e32 v68, v68, v70
	v_add_f32_e32 v66, v67, v66
	v_add_f32_e32 v64, v64, v68
	v_add_f32_e32 v65, v66, v65
	v_add_f32_e32 v64, v65, v64
	ds_bpermute_b32 v65, v226, v64
	s_waitcnt lgkmcnt(0)
	v_add_f32_e32 v64, v64, v65
	ds_bpermute_b32 v65, v227, v64
	s_and_saveexec_b64 s[8:9], s[40:41]
	s_cbranch_execz .LBB0_1049
	s_waitcnt lgkmcnt(0)
	v_add_f32_e32 v64, v64, v65
	v_mul_f32_e32 v64, 0x4b800000, v64
	v_trunc_f32_e32 v64, v64
	v_mul_f32_e32 v65, 0x2f800000, v64
	v_floor_f32_e32 v65, v65
	v_fmac_f32_e32 v64, 0xcf800000, v65
	v_cvt_u32_f32_e32 v64, v64
	v_cvt_u32_f32_e32 v65, v65
	global_atomic_add_x2 v[134:135], v[64:65], off offset:384
.LBB0_1049:
	s_or_b64 exec, exec, s[8:9]
	v_lshlrev_b32_e32 v68, 16, v154
	v_and_b32_e32 v69, 0xffff0000, v154
	v_pk_add_f32 v[60:61], v[60:61], v[68:69]
	v_lshlrev_b32_e32 v68, 16, v155
	v_and_b32_e32 v69, 0xffff0000, v155
	v_pk_add_f32 v[62:63], v[62:63], v[68:69]
	v_lshlrev_b32_e32 v68, 16, v156
	v_and_b32_e32 v69, 0xffff0000, v156
	v_pk_add_f32 v[68:69], v[56:57], v[68:69]
	v_lshlrev_b32_e32 v56, 16, v157
	v_and_b32_e32 v57, 0xffff0000, v157
	s_mov_b64 s[8:9], 0x80000
	v_pk_add_f32 v[70:71], v[58:59], v[56:57]
	s_waitcnt lgkmcnt(0)
	v_lshl_add_u64 v[64:65], v[210:211], 0, s[8:9]
	v_cvt_pk_bf16_f32 v56, v60, v61
	v_cvt_pk_bf16_f32 v57, v62, v63
	v_cvt_pk_bf16_f32 v58, v68, v69
	v_cvt_pk_bf16_f32 v59, v70, v71
	global_store_dwordx4 v[64:65], v[56:59], off sc1
	v_lshlrev_b32_e32 v64, 16, v146
	v_and_b32_e32 v65, 0xffff0000, v146
	v_pk_add_f32 v[52:53], v[52:53], v[64:65]
	v_lshlrev_b32_e32 v64, 16, v147
	v_and_b32_e32 v65, 0xffff0000, v147
	v_pk_add_f32 v[54:55], v[54:55], v[64:65]
	v_lshlrev_b32_e32 v64, 16, v148
	v_and_b32_e32 v65, 0xffff0000, v148
	v_pk_add_f32 v[64:65], v[48:49], v[64:65]
	v_lshlrev_b32_e32 v48, 16, v149
	v_and_b32_e32 v49, 0xffff0000, v149
	s_mov_b64 s[8:9], 0x80100
	v_pk_mul_f32 v[56:57], v[60:61], v[60:61]
	v_pk_mul_f32 v[60:61], v[68:69], v[68:69]
	v_pk_add_f32 v[68:69], v[50:51], v[48:49]
	v_lshl_add_u64 v[66:67], v[210:211], 0, s[8:9]
	v_cvt_pk_bf16_f32 v48, v52, v53
	v_cvt_pk_bf16_f32 v49, v54, v55
	v_cvt_pk_bf16_f32 v50, v64, v65
	v_cvt_pk_bf16_f32 v51, v68, v69
	global_store_dwordx4 v[66:67], v[48:51], off sc1
	v_pk_mul_f32 v[58:59], v[62:63], v[62:63]
	v_pk_mul_f32 v[62:63], v[70:71], v[70:71]
	v_pk_mul_f32 v[48:49], v[52:53], v[52:53]
	v_pk_mul_f32 v[50:51], v[54:55], v[54:55]
	v_add_f32_e32 v48, v48, v49
	v_add_f32_e32 v50, v50, v51
	v_pk_mul_f32 v[52:53], v[64:65], v[64:65]
	v_pk_mul_f32 v[54:55], v[68:69], v[68:69]
	v_add_f32_e32 v48, v48, v50
	v_add_f32_e32 v49, v62, v63
	v_add_f32_e32 v50, v60, v61
	v_add_f32_e32 v54, v54, v55
	v_add_f32_e32 v52, v52, v53
	v_add_f32_e32 v49, v50, v49
	v_add_f32_e32 v50, v58, v59
	v_add_f32_e32 v51, v56, v57
	v_add_f32_e32 v52, v52, v54
	v_add_f32_e32 v50, v51, v50
	v_add_f32_e32 v48, v48, v52
	v_add_f32_e32 v49, v50, v49
	v_add_f32_e32 v48, v49, v48
	ds_bpermute_b32 v49, v226, v48
	s_waitcnt lgkmcnt(0)
	v_add_f32_e32 v48, v48, v49
	ds_bpermute_b32 v49, v227, v48
	s_and_saveexec_b64 s[8:9], s[40:41]
	s_cbranch_execz .LBB0_1051
	s_waitcnt lgkmcnt(0)
	v_add_f32_e32 v48, v48, v49
	v_mul_f32_e32 v48, 0x4b800000, v48
	v_trunc_f32_e32 v48, v48
	v_mul_f32_e32 v49, 0x2f800000, v48
	v_floor_f32_e32 v49, v49
	v_fmac_f32_e32 v48, 0xcf800000, v49
	v_cvt_u32_f32_e32 v48, v48
	v_cvt_u32_f32_e32 v49, v49
	global_atomic_add_x2 v[134:135], v[48:49], off offset:1024
.LBB0_1051:
	s_or_b64 exec, exec, s[8:9]
	v_lshlrev_b32_e32 v52, 16, v138
	v_and_b32_e32 v53, 0xffff0000, v138
	v_pk_add_f32 v[44:45], v[44:45], v[52:53]
	v_lshlrev_b32_e32 v52, 16, v139
	v_and_b32_e32 v53, 0xffff0000, v139
	v_pk_add_f32 v[46:47], v[46:47], v[52:53]
	v_lshlrev_b32_e32 v52, 16, v140
	v_and_b32_e32 v53, 0xffff0000, v140
	v_pk_add_f32 v[52:53], v[40:41], v[52:53]
	v_lshlrev_b32_e32 v40, 16, v141
	v_and_b32_e32 v41, 0xffff0000, v141
	s_mov_b64 s[8:9], 0x90000
	v_pk_add_f32 v[54:55], v[42:43], v[40:41]
	s_waitcnt lgkmcnt(0)
	v_lshl_add_u64 v[48:49], v[210:211], 0, s[8:9]
	v_cvt_pk_bf16_f32 v40, v44, v45
	v_cvt_pk_bf16_f32 v41, v46, v47
	v_cvt_pk_bf16_f32 v42, v52, v53
	v_cvt_pk_bf16_f32 v43, v54, v55
	global_store_dwordx4 v[48:49], v[40:43], off sc1
	v_lshlrev_b32_e32 v48, 16, v130
	v_and_b32_e32 v49, 0xffff0000, v130
	v_pk_add_f32 v[36:37], v[36:37], v[48:49]
	v_lshlrev_b32_e32 v48, 16, v131
	v_and_b32_e32 v49, 0xffff0000, v131
	v_pk_add_f32 v[38:39], v[38:39], v[48:49]
	v_lshlrev_b32_e32 v48, 16, v132
	v_and_b32_e32 v49, 0xffff0000, v132
	v_pk_add_f32 v[48:49], v[32:33], v[48:49]
	v_lshlrev_b32_e32 v32, 16, v133
	v_and_b32_e32 v33, 0xffff0000, v133
	s_mov_b64 s[8:9], 0x90100
	v_pk_mul_f32 v[40:41], v[44:45], v[44:45]
	v_pk_mul_f32 v[44:45], v[52:53], v[52:53]
	v_pk_add_f32 v[52:53], v[34:35], v[32:33]
	v_lshl_add_u64 v[50:51], v[210:211], 0, s[8:9]
	v_cvt_pk_bf16_f32 v32, v36, v37
	v_cvt_pk_bf16_f32 v33, v38, v39
	v_cvt_pk_bf16_f32 v34, v48, v49
	v_cvt_pk_bf16_f32 v35, v52, v53
	global_store_dwordx4 v[50:51], v[32:35], off sc1
	v_pk_mul_f32 v[42:43], v[46:47], v[46:47]
	v_pk_mul_f32 v[46:47], v[54:55], v[54:55]
	v_pk_mul_f32 v[32:33], v[36:37], v[36:37]
	v_pk_mul_f32 v[34:35], v[38:39], v[38:39]
	v_add_f32_e32 v32, v32, v33
	v_add_f32_e32 v34, v34, v35
	v_pk_mul_f32 v[36:37], v[48:49], v[48:49]
	v_pk_mul_f32 v[38:39], v[52:53], v[52:53]
	v_add_f32_e32 v32, v32, v34
	v_add_f32_e32 v33, v46, v47
	v_add_f32_e32 v34, v44, v45
	v_add_f32_e32 v38, v38, v39
	v_add_f32_e32 v36, v36, v37
	v_add_f32_e32 v33, v34, v33
	v_add_f32_e32 v34, v42, v43
	v_add_f32_e32 v35, v40, v41
	v_add_f32_e32 v36, v36, v38
	v_add_f32_e32 v34, v35, v34
	v_add_f32_e32 v32, v32, v36
	v_add_f32_e32 v33, v34, v33
	v_add_f32_e32 v32, v33, v32
	ds_bpermute_b32 v33, v226, v32
	s_waitcnt lgkmcnt(0)
	v_add_f32_e32 v32, v32, v33
	ds_bpermute_b32 v33, v227, v32
	s_and_saveexec_b64 s[8:9], s[40:41]
	s_cbranch_execz .LBB0_1053
	s_waitcnt lgkmcnt(0)
	v_add_f32_e32 v32, v32, v33
	v_mul_f32_e32 v32, 0x4b800000, v32
	v_trunc_f32_e32 v32, v32
	v_mul_f32_e32 v33, 0x2f800000, v32
	v_floor_f32_e32 v33, v33
	v_fmac_f32_e32 v32, 0xcf800000, v33
	v_cvt_u32_f32_e32 v32, v32
	v_cvt_u32_f32_e32 v33, v33
	global_atomic_add_x2 v[134:135], v[32:33], off offset:1152
.LBB0_1053:
	s_or_b64 exec, exec, s[8:9]
	v_lshlrev_b32_e32 v36, 16, v116
	v_and_b32_e32 v37, 0xffff0000, v116
	v_pk_add_f32 v[28:29], v[28:29], v[36:37]
	v_lshlrev_b32_e32 v36, 16, v117
	v_and_b32_e32 v37, 0xffff0000, v117
	v_pk_add_f32 v[30:31], v[30:31], v[36:37]
	v_lshlrev_b32_e32 v36, 16, v118
	v_and_b32_e32 v37, 0xffff0000, v118
	v_pk_add_f32 v[36:37], v[24:25], v[36:37]
	v_lshlrev_b32_e32 v24, 16, v119
	v_and_b32_e32 v25, 0xffff0000, v119
	s_mov_b64 s[8:9], 0xa0000
	v_pk_add_f32 v[38:39], v[26:27], v[24:25]
	s_waitcnt lgkmcnt(0)
	v_lshl_add_u64 v[32:33], v[210:211], 0, s[8:9]
	v_cvt_pk_bf16_f32 v24, v28, v29
	v_cvt_pk_bf16_f32 v25, v30, v31
	v_cvt_pk_bf16_f32 v26, v36, v37
	v_cvt_pk_bf16_f32 v27, v38, v39
	global_store_dwordx4 v[32:33], v[24:27], off sc1
	v_lshlrev_b32_e32 v32, 16, v104
	v_and_b32_e32 v33, 0xffff0000, v104
	v_pk_add_f32 v[20:21], v[20:21], v[32:33]
	v_lshlrev_b32_e32 v32, 16, v105
	v_and_b32_e32 v33, 0xffff0000, v105
	v_pk_add_f32 v[22:23], v[22:23], v[32:33]
	v_lshlrev_b32_e32 v32, 16, v106
	v_and_b32_e32 v33, 0xffff0000, v106
	v_pk_add_f32 v[32:33], v[16:17], v[32:33]
	v_lshlrev_b32_e32 v16, 16, v107
	v_and_b32_e32 v17, 0xffff0000, v107
	s_mov_b64 s[8:9], 0xa0100
	v_pk_mul_f32 v[24:25], v[28:29], v[28:29]
	v_pk_mul_f32 v[28:29], v[36:37], v[36:37]
	v_pk_add_f32 v[36:37], v[18:19], v[16:17]
	v_lshl_add_u64 v[34:35], v[210:211], 0, s[8:9]
	v_cvt_pk_bf16_f32 v16, v20, v21
	v_cvt_pk_bf16_f32 v17, v22, v23
	v_cvt_pk_bf16_f32 v18, v32, v33
	v_cvt_pk_bf16_f32 v19, v36, v37
	global_store_dwordx4 v[34:35], v[16:19], off sc1
	v_pk_mul_f32 v[26:27], v[30:31], v[30:31]
	v_pk_mul_f32 v[30:31], v[38:39], v[38:39]
	v_pk_mul_f32 v[16:17], v[20:21], v[20:21]
	v_pk_mul_f32 v[18:19], v[22:23], v[22:23]
	v_add_f32_e32 v16, v16, v17
	v_add_f32_e32 v18, v18, v19
	v_pk_mul_f32 v[20:21], v[32:33], v[32:33]
	v_pk_mul_f32 v[22:23], v[36:37], v[36:37]
	v_add_f32_e32 v16, v16, v18
	v_add_f32_e32 v17, v30, v31
	v_add_f32_e32 v18, v28, v29
	v_add_f32_e32 v22, v22, v23
	v_add_f32_e32 v20, v20, v21
	v_add_f32_e32 v17, v18, v17
	v_add_f32_e32 v18, v26, v27
	v_add_f32_e32 v19, v24, v25
	v_add_f32_e32 v20, v20, v22
	v_add_f32_e32 v18, v19, v18
	v_add_f32_e32 v16, v16, v20
	v_add_f32_e32 v17, v18, v17
	v_add_f32_e32 v16, v17, v16
	ds_bpermute_b32 v17, v226, v16
	s_waitcnt lgkmcnt(0)
	v_add_f32_e32 v16, v16, v17
	ds_bpermute_b32 v17, v227, v16
	s_and_saveexec_b64 s[8:9], s[40:41]
	s_cbranch_execz .LBB0_1055
	s_waitcnt lgkmcnt(0)
	v_add_f32_e32 v16, v16, v17
	v_mul_f32_e32 v16, 0x4b800000, v16
	v_trunc_f32_e32 v16, v16
	v_mul_f32_e32 v17, 0x2f800000, v16
	v_floor_f32_e32 v17, v17
	v_fmac_f32_e32 v16, 0xcf800000, v17
	v_cvt_u32_f32_e32 v16, v16
	v_cvt_u32_f32_e32 v17, v17
	global_atomic_add_x2 v[134:135], v[16:17], off offset:1280
.LBB0_1055:
	s_or_b64 exec, exec, s[8:9]
	v_lshlrev_b32_e32 v20, 16, v96
	v_and_b32_e32 v21, 0xffff0000, v96
	v_pk_add_f32 v[12:13], v[12:13], v[20:21]
	v_lshlrev_b32_e32 v20, 16, v97
	v_and_b32_e32 v21, 0xffff0000, v97
	v_pk_add_f32 v[14:15], v[14:15], v[20:21]
	v_lshlrev_b32_e32 v20, 16, v98
	v_and_b32_e32 v21, 0xffff0000, v98
	v_pk_add_f32 v[20:21], v[8:9], v[20:21]
	v_lshlrev_b32_e32 v8, 16, v99
	v_and_b32_e32 v9, 0xffff0000, v99
	s_mov_b64 s[8:9], 0xb0000
	v_pk_add_f32 v[22:23], v[10:11], v[8:9]
	s_waitcnt lgkmcnt(0)
	v_lshl_add_u64 v[16:17], v[210:211], 0, s[8:9]
	v_cvt_pk_bf16_f32 v8, v12, v13
	v_cvt_pk_bf16_f32 v9, v14, v15
	v_cvt_pk_bf16_f32 v10, v20, v21
	v_cvt_pk_bf16_f32 v11, v22, v23
	global_store_dwordx4 v[16:17], v[8:11], off sc1
	v_lshlrev_b32_e32 v16, 16, v88
	v_and_b32_e32 v17, 0xffff0000, v88
	v_pk_add_f32 v[4:5], v[4:5], v[16:17]
	v_lshlrev_b32_e32 v16, 16, v89
	v_and_b32_e32 v17, 0xffff0000, v89
	v_pk_add_f32 v[6:7], v[6:7], v[16:17]
	v_lshlrev_b32_e32 v16, 16, v90
	v_and_b32_e32 v17, 0xffff0000, v90
	v_pk_add_f32 v[16:17], v[0:1], v[16:17]
	v_lshlrev_b32_e32 v0, 16, v91
	v_and_b32_e32 v1, 0xffff0000, v91
	s_mov_b64 s[8:9], 0xb0100
	v_pk_mul_f32 v[8:9], v[12:13], v[12:13]
	v_pk_mul_f32 v[12:13], v[20:21], v[20:21]
	v_pk_add_f32 v[20:21], v[2:3], v[0:1]
	v_lshl_add_u64 v[18:19], v[210:211], 0, s[8:9]
	v_cvt_pk_bf16_f32 v0, v4, v5
	v_cvt_pk_bf16_f32 v1, v6, v7
	v_cvt_pk_bf16_f32 v2, v16, v17
	v_cvt_pk_bf16_f32 v3, v20, v21
	global_store_dwordx4 v[18:19], v[0:3], off sc1
	v_pk_mul_f32 v[10:11], v[14:15], v[14:15]
	v_pk_mul_f32 v[14:15], v[22:23], v[22:23]
	v_pk_mul_f32 v[0:1], v[4:5], v[4:5]
	v_pk_mul_f32 v[2:3], v[6:7], v[6:7]
	v_add_f32_e32 v0, v0, v1
	v_add_f32_e32 v2, v2, v3
	v_pk_mul_f32 v[4:5], v[16:17], v[16:17]
	v_pk_mul_f32 v[6:7], v[20:21], v[20:21]
	v_add_f32_e32 v0, v0, v2
	v_add_f32_e32 v1, v14, v15
	v_add_f32_e32 v2, v12, v13
	v_add_f32_e32 v6, v6, v7
	v_add_f32_e32 v4, v4, v5
	v_add_f32_e32 v1, v2, v1
	v_add_f32_e32 v2, v10, v11
	v_add_f32_e32 v3, v8, v9
	v_add_f32_e32 v4, v4, v6
	v_add_f32_e32 v2, v3, v2
	v_add_f32_e32 v0, v0, v4
	v_add_f32_e32 v1, v2, v1
	v_add_f32_e32 v0, v1, v0
	ds_bpermute_b32 v1, v226, v0
	s_waitcnt lgkmcnt(0)
	v_add_f32_e32 v0, v0, v1
	ds_bpermute_b32 v1, v227, v0
	s_and_saveexec_b64 s[8:9], s[40:41]
	s_cbranch_execz .LBB0_1057
	s_waitcnt lgkmcnt(0)
	v_add_f32_e32 v0, v0, v1
	v_mul_f32_e32 v0, 0x4b800000, v0
	v_trunc_f32_e32 v0, v0
	v_mul_f32_e32 v1, 0x2f800000, v0
	v_floor_f32_e32 v1, v1
	v_fmac_f32_e32 v0, 0xcf800000, v1
	v_cvt_u32_f32_e32 v0, v0
	v_cvt_u32_f32_e32 v1, v1
	global_atomic_add_x2 v[134:135], v[0:1], off offset:1408

.LBB0_1387:
	v_lshl_add_u32 v210, s72, 8, v222
	v_ashrrev_i32_e32 v211, 31, v210
	v_lshl_or_b32 v88, s33, 8, v224
	v_lshlrev_b64 v[90:91], 12, v[210:211]
	v_lshl_add_u64 v[90:91], s[30:31], 0, v[90:91]
	v_ashrrev_i32_e32 v89, 31, v88
	v_lshl_add_u64 v[212:213], v[88:89], 1, v[90:91]
	global_load_dwordx4 v[228:231], v[212:213], off
	global_load_dwordx4 v[186:189], v[212:213], off offset:256
	v_add_co_u32_e32 v88, vcc, 0x10000, v212
	v_readlane_b32 s8, v237, 51
	s_nop 0
	v_addc_co_u32_e32 v89, vcc, 0, v213, vcc
	v_readlane_b32 s11, v237, 54
	global_load_dwordx4 v[182:185], v[88:89], off
	global_load_dwordx4 v[178:181], v[88:89], off offset:256
	v_add_co_u32_e32 v88, vcc, s11, v212
	s_mov_b32 s8, 0x80000
	s_nop 0
	v_addc_co_u32_e32 v89, vcc, 0, v213, vcc
	global_load_dwordx4 v[174:177], v[88:89], off
	global_load_dwordx4 v[170:173], v[88:89], off offset:256
	v_add_co_u32_e32 v88, vcc, 0x30000, v212
	v_and_b32_e32 v227, 64, v214
	s_nop 0
	v_addc_co_u32_e32 v89, vcc, 0, v213, vcc
	global_load_dwordx4 v[166:169], v[88:89], off
	global_load_dwordx4 v[162:165], v[88:89], off offset:256
	v_add_co_u32_e32 v88, vcc, s8, v212
	s_mov_b32 s8, 0xb0000
	s_nop 0
	v_addc_co_u32_e32 v89, vcc, 0, v213, vcc
	global_load_dwordx4 v[154:157], v[88:89], off
	global_load_dwordx4 v[146:149], v[88:89], off offset:256
	v_add_co_u32_e32 v88, vcc, 0x90000, v212
	v_xor_b32_e32 v226, 16, v214
	s_nop 0
	v_addc_co_u32_e32 v89, vcc, 0, v213, vcc
	global_load_dwordx4 v[138:141], v[88:89], off
	global_load_dwordx4 v[130:133], v[88:89], off offset:256
	v_add_co_u32_e32 v88, vcc, 0xa0000, v212
	v_add_u32_e32 v227, 64, v227
	s_nop 0
	v_addc_co_u32_e32 v89, vcc, 0, v213, vcc
	global_load_dwordx4 v[116:119], v[88:89], off
	global_load_dwordx4 v[104:107], v[88:89], off offset:256
	v_add_co_u32_e32 v88, vcc, s8, v212
	v_xor_b32_e32 v232, 32, v214
	s_nop 0
	v_addc_co_u32_e32 v89, vcc, 0, v213, vcc
	global_load_dwordx4 v[92:95], v[88:89], off
	s_nop 0
	global_load_dwordx4 v[88:91], v[88:89], off offset:256
	v_cmp_lt_i32_e32 vcc, v226, v227
	v_readlane_b32 s9, v237, 52
	v_readlane_b32 s10, v237, 53
	v_cndmask_b32_e32 v226, v214, v226, vcc
	v_cmp_lt_i32_e32 vcc, v232, v227
	v_lshlrev_b32_e32 v226, 2, v226
	s_waitcnt vmcnt(0)
	v_and_b32_e32 v233, 0xffff0000, v228
	v_cndmask_b32_e32 v227, v214, v232, vcc
	v_lshlrev_b32_e32 v232, 16, v228
	v_lshlrev_b32_e32 v228, 16, v229
	v_and_b32_e32 v229, 0xffff0000, v229
	v_pk_add_f32 v[160:161], v[160:161], v[228:229]
	v_lshlrev_b32_e32 v228, 16, v230
	v_and_b32_e32 v229, 0xffff0000, v230
	v_pk_add_f32 v[228:229], v[150:151], v[228:229]
	v_lshlrev_b32_e32 v150, 16, v231
	v_and_b32_e32 v151, 0xffff0000, v231
	v_pk_add_f32 v[158:159], v[158:159], v[232:233]
	v_pk_add_f32 v[230:231], v[152:153], v[150:151]
	v_cvt_pk_bf16_f32 v150, v158, v159
	v_cvt_pk_bf16_f32 v151, v160, v161
	v_cvt_pk_bf16_f32 v152, v228, v229
	v_cvt_pk_bf16_f32 v153, v230, v231
	global_store_dwordx4 v[212:213], v[150:153], off sc1
	v_lshlrev_b32_e32 v227, 2, v227
	s_nop 0
	v_pk_mul_f32 v[150:151], v[158:159], v[158:159]
	v_pk_mul_f32 v[158:159], v[228:229], v[228:229]
	v_lshlrev_b32_e32 v228, 16, v186
	v_and_b32_e32 v229, 0xffff0000, v186
	v_lshlrev_b32_e32 v186, 16, v187
	v_and_b32_e32 v187, 0xffff0000, v187
	v_pk_add_f32 v[144:145], v[144:145], v[186:187]
	v_lshlrev_b32_e32 v186, 16, v188
	v_and_b32_e32 v187, 0xffff0000, v188
	v_pk_add_f32 v[186:187], v[134:135], v[186:187]
	v_lshlrev_b32_e32 v134, 16, v189
	v_and_b32_e32 v135, 0xffff0000, v189
	v_pk_add_f32 v[142:143], v[142:143], v[228:229]
	v_pk_add_f32 v[188:189], v[136:137], v[134:135]
	v_cvt_pk_bf16_f32 v134, v142, v143
	v_cvt_pk_bf16_f32 v135, v144, v145
	v_cvt_pk_bf16_f32 v136, v186, v187
	v_cvt_pk_bf16_f32 v137, v188, v189
	global_store_dwordx4 v[212:213], v[134:137], off offset:256 sc1
	v_pk_mul_f32 v[152:153], v[160:161], v[160:161]
	v_pk_mul_f32 v[160:161], v[230:231], v[230:231]
	v_pk_mul_f32 v[134:135], v[142:143], v[142:143]
	v_pk_mul_f32 v[136:137], v[144:145], v[144:145]
	v_add_f32_e32 v134, v134, v135
	v_add_f32_e32 v136, v136, v137
	v_pk_mul_f32 v[142:143], v[186:187], v[186:187]
	v_pk_mul_f32 v[144:145], v[188:189], v[188:189]
	v_add_f32_e32 v134, v134, v136
	v_add_f32_e32 v135, v160, v161
	v_add_f32_e32 v136, v158, v159
	v_add_f32_e32 v144, v144, v145
	v_add_f32_e32 v142, v142, v143
	v_add_f32_e32 v135, v136, v135
	v_add_f32_e32 v136, v152, v153
	v_add_f32_e32 v137, v150, v151
	v_add_f32_e32 v142, v142, v144
	v_add_f32_e32 v136, v137, v136
	v_add_f32_e32 v134, v134, v142
	v_add_f32_e32 v135, v136, v135
	v_add_f32_e32 v134, v135, v134
	ds_bpermute_b32 v135, v226, v134
	s_waitcnt lgkmcnt(0)
	v_add_f32_e32 v134, v134, v135
	ds_bpermute_b32 v135, v227, v134
	s_and_saveexec_b64 s[8:9], s[40:41]
	s_cbranch_execz .LBB0_1389
	s_waitcnt lgkmcnt(0)
	v_add_f32_e32 v134, v134, v135
	v_mul_f32_e32 v134, 0x4b800000, v134
	v_trunc_f32_e32 v134, v134
	v_mul_f32_e32 v135, 0x2f800000, v134
	v_floor_f32_e32 v135, v135
	v_fmac_f32_e32 v134, 0xcf800000, v135
	v_cvt_u32_f32_e32 v134, v134
	v_cvt_u32_f32_e32 v135, v135
	v_lshl_add_u64 v[136:137], v[210:211], 3, s[46:47]
	global_atomic_add_x2 v[136:137], v[134:135], off
.LBB0_1389:
	s_or_b64 exec, exec, s[8:9]
	v_lshlrev_b32_e32 v142, 16, v182
	v_and_b32_e32 v143, 0xffff0000, v182
	v_pk_add_f32 v[124:125], v[124:125], v[142:143]
	v_lshlrev_b32_e32 v142, 16, v183
	v_and_b32_e32 v143, 0xffff0000, v183
	v_pk_add_f32 v[126:127], v[126:127], v[142:143]
	v_lshlrev_b32_e32 v142, 16, v184
	v_and_b32_e32 v143, 0xffff0000, v184
	v_pk_add_f32 v[142:143], v[120:121], v[142:143]
	v_lshlrev_b32_e32 v120, 16, v185
	v_and_b32_e32 v121, 0xffff0000, v185
	s_mov_b64 s[8:9], 0x10000
	v_pk_add_f32 v[144:145], v[122:123], v[120:121]
	s_waitcnt lgkmcnt(0)
	v_lshl_add_u64 v[134:135], v[212:213], 0, s[8:9]
	v_cvt_pk_bf16_f32 v120, v124, v125
	v_cvt_pk_bf16_f32 v121, v126, v127
	v_cvt_pk_bf16_f32 v122, v142, v143
	v_cvt_pk_bf16_f32 v123, v144, v145
	global_store_dwordx4 v[134:135], v[120:123], off sc1
	v_lshlrev_b32_e32 v134, 16, v178
	v_and_b32_e32 v135, 0xffff0000, v178
	v_pk_add_f32 v[112:113], v[112:113], v[134:135]
	v_lshlrev_b32_e32 v134, 16, v179
	v_and_b32_e32 v135, 0xffff0000, v179
	v_pk_add_f32 v[114:115], v[114:115], v[134:135]
	v_lshlrev_b32_e32 v134, 16, v180
	v_and_b32_e32 v135, 0xffff0000, v180
	v_pk_add_f32 v[134:135], v[108:109], v[134:135]
	v_lshlrev_b32_e32 v108, 16, v181
	v_and_b32_e32 v109, 0xffff0000, v181
	s_mov_b64 s[8:9], 0x10100
	v_pk_mul_f32 v[120:121], v[124:125], v[124:125]
	v_pk_mul_f32 v[124:125], v[142:143], v[142:143]
	v_pk_add_f32 v[142:143], v[110:111], v[108:109]
	v_lshl_add_u64 v[136:137], v[212:213], 0, s[8:9]
	v_cvt_pk_bf16_f32 v108, v112, v113
	v_cvt_pk_bf16_f32 v109, v114, v115
	v_cvt_pk_bf16_f32 v110, v134, v135
	v_cvt_pk_bf16_f32 v111, v142, v143
	global_store_dwordx4 v[136:137], v[108:111], off sc1
	v_pk_mul_f32 v[122:123], v[126:127], v[126:127]
	v_pk_mul_f32 v[126:127], v[144:145], v[144:145]
	v_pk_mul_f32 v[108:109], v[112:113], v[112:113]
	v_pk_mul_f32 v[110:111], v[114:115], v[114:115]
	v_add_f32_e32 v108, v108, v109
	v_add_f32_e32 v110, v110, v111
	v_pk_mul_f32 v[112:113], v[134:135], v[134:135]
	v_pk_mul_f32 v[114:115], v[142:143], v[142:143]
	v_add_f32_e32 v108, v108, v110
	v_add_f32_e32 v109, v126, v127
	v_add_f32_e32 v110, v124, v125
	v_add_f32_e32 v114, v114, v115
	v_add_f32_e32 v112, v112, v113
	v_add_f32_e32 v109, v110, v109
	v_add_f32_e32 v110, v122, v123
	v_add_f32_e32 v111, v120, v121
	v_add_f32_e32 v112, v112, v114
	v_add_f32_e32 v110, v111, v110
	v_add_f32_e32 v108, v108, v112
	v_add_f32_e32 v109, v110, v109
	v_add_f32_e32 v108, v109, v108
	ds_bpermute_b32 v109, v226, v108
	s_waitcnt lgkmcnt(0)
	v_add_f32_e32 v108, v108, v109
	ds_bpermute_b32 v109, v227, v108
	s_and_saveexec_b64 s[8:9], s[40:41]
	s_cbranch_execz .LBB0_1391
	s_waitcnt lgkmcnt(0)
	v_add_f32_e32 v108, v108, v109
	v_mul_f32_e32 v108, 0x4b800000, v108
	v_trunc_f32_e32 v108, v108
	v_mul_f32_e32 v109, 0x2f800000, v108
	v_floor_f32_e32 v109, v109
	v_fmac_f32_e32 v108, 0xcf800000, v109
	v_cvt_u32_f32_e32 v108, v108
	v_cvt_u32_f32_e32 v109, v109
	v_lshl_add_u64 v[110:111], v[210:211], 3, s[46:47]
	global_atomic_add_x2 v[110:111], v[108:109], off offset:128
.LBB0_1391:
	s_or_b64 exec, exec, s[8:9]
	v_lshlrev_b32_e32 v112, 16, v174
	v_and_b32_e32 v113, 0xffff0000, v174
	v_pk_add_f32 v[100:101], v[100:101], v[112:113]
	v_lshlrev_b32_e32 v112, 16, v175
	v_and_b32_e32 v113, 0xffff0000, v175
	v_pk_add_f32 v[102:103], v[102:103], v[112:113]
	v_lshlrev_b32_e32 v112, 16, v176
	v_and_b32_e32 v113, 0xffff0000, v176
	v_pk_add_f32 v[112:113], v[96:97], v[112:113]
	v_lshlrev_b32_e32 v96, 16, v177
	v_and_b32_e32 v97, 0xffff0000, v177
	s_mov_b64 s[8:9], 0x20000
	v_pk_add_f32 v[114:115], v[98:99], v[96:97]
	s_waitcnt lgkmcnt(0)
	v_lshl_add_u64 v[108:109], v[212:213], 0, s[8:9]
	v_cvt_pk_bf16_f32 v96, v100, v101
	v_cvt_pk_bf16_f32 v97, v102, v103
	v_cvt_pk_bf16_f32 v98, v112, v113
	v_cvt_pk_bf16_f32 v99, v114, v115
	global_store_dwordx4 v[108:109], v[96:99], off sc1
	v_lshlrev_b32_e32 v108, 16, v170
	v_and_b32_e32 v109, 0xffff0000, v170
	v_pk_add_f32 v[84:85], v[84:85], v[108:109]
	v_lshlrev_b32_e32 v108, 16, v171
	v_and_b32_e32 v109, 0xffff0000, v171
	v_pk_add_f32 v[86:87], v[86:87], v[108:109]
	v_lshlrev_b32_e32 v108, 16, v172
	v_and_b32_e32 v109, 0xffff0000, v172
	v_pk_add_f32 v[108:109], v[80:81], v[108:109]
	v_lshlrev_b32_e32 v80, 16, v173
	v_and_b32_e32 v81, 0xffff0000, v173
	s_mov_b64 s[8:9], 0x20100
	v_pk_mul_f32 v[96:97], v[100:101], v[100:101]
	v_pk_mul_f32 v[100:101], v[112:113], v[112:113]
	v_pk_add_f32 v[112:113], v[82:83], v[80:81]
	v_lshl_add_u64 v[110:111], v[212:213], 0, s[8:9]
	v_cvt_pk_bf16_f32 v80, v84, v85
	v_cvt_pk_bf16_f32 v81, v86, v87
	v_cvt_pk_bf16_f32 v82, v108, v109
	v_cvt_pk_bf16_f32 v83, v112, v113
	global_store_dwordx4 v[110:111], v[80:83], off sc1
	v_pk_mul_f32 v[98:99], v[102:103], v[102:103]
	v_pk_mul_f32 v[102:103], v[114:115], v[114:115]
	v_pk_mul_f32 v[80:81], v[84:85], v[84:85]
	v_pk_mul_f32 v[82:83], v[86:87], v[86:87]
	v_add_f32_e32 v80, v80, v81
	v_add_f32_e32 v82, v82, v83
	v_pk_mul_f32 v[84:85], v[108:109], v[108:109]
	v_pk_mul_f32 v[86:87], v[112:113], v[112:113]
	v_add_f32_e32 v80, v80, v82
	v_add_f32_e32 v81, v102, v103
	v_add_f32_e32 v82, v100, v101
	v_add_f32_e32 v86, v86, v87
	v_add_f32_e32 v84, v84, v85
	v_add_f32_e32 v81, v82, v81
	v_add_f32_e32 v82, v98, v99
	v_add_f32_e32 v83, v96, v97
	v_add_f32_e32 v84, v84, v86
	v_add_f32_e32 v82, v83, v82
	v_add_f32_e32 v80, v80, v84
	v_add_f32_e32 v81, v82, v81
	v_add_f32_e32 v80, v81, v80
	ds_bpermute_b32 v81, v226, v80
	s_waitcnt lgkmcnt(0)
	v_add_f32_e32 v80, v80, v81
	ds_bpermute_b32 v81, v227, v80
	s_and_saveexec_b64 s[8:9], s[40:41]
	s_mov_b64 s[28:29], s[34:35]
	s_cbranch_execz .LBB0_1393
	s_waitcnt lgkmcnt(0)
	v_add_f32_e32 v80, v80, v81
	v_mul_f32_e32 v80, 0x4b800000, v80
	v_trunc_f32_e32 v80, v80
	v_mul_f32_e32 v81, 0x2f800000, v80
	v_floor_f32_e32 v81, v81
	v_fmac_f32_e32 v80, 0xcf800000, v81
	v_cvt_u32_f32_e32 v80, v80
	v_cvt_u32_f32_e32 v81, v81
	v_lshl_add_u64 v[82:83], v[210:211], 3, s[46:47]
	global_atomic_add_x2 v[82:83], v[80:81], off offset:256
.LBB0_1393:
	s_or_b64 exec, exec, s[8:9]
	v_lshlrev_b32_e32 v84, 16, v166
	v_and_b32_e32 v85, 0xffff0000, v166
	v_pk_add_f32 v[76:77], v[76:77], v[84:85]
	v_lshlrev_b32_e32 v84, 16, v167
	v_and_b32_e32 v85, 0xffff0000, v167
	v_pk_add_f32 v[78:79], v[78:79], v[84:85]
	v_lshlrev_b32_e32 v84, 16, v168
	v_and_b32_e32 v85, 0xffff0000, v168
	v_pk_add_f32 v[84:85], v[72:73], v[84:85]
	v_lshlrev_b32_e32 v72, 16, v169
	v_and_b32_e32 v73, 0xffff0000, v169
	s_mov_b64 s[8:9], 0x30000
	v_pk_add_f32 v[86:87], v[74:75], v[72:73]
	s_waitcnt lgkmcnt(0)
	v_lshl_add_u64 v[80:81], v[212:213], 0, s[8:9]
	v_cvt_pk_bf16_f32 v72, v76, v77
	v_cvt_pk_bf16_f32 v73, v78, v79
	v_cvt_pk_bf16_f32 v74, v84, v85
	v_cvt_pk_bf16_f32 v75, v86, v87
	global_store_dwordx4 v[80:81], v[72:75], off sc1
	v_lshlrev_b32_e32 v80, 16, v162
	v_and_b32_e32 v81, 0xffff0000, v162
	v_pk_add_f32 v[68:69], v[68:69], v[80:81]
	v_lshlrev_b32_e32 v80, 16, v163
	v_and_b32_e32 v81, 0xffff0000, v163
	v_pk_add_f32 v[70:71], v[70:71], v[80:81]
	v_lshlrev_b32_e32 v80, 16, v164
	v_and_b32_e32 v81, 0xffff0000, v164
	v_pk_add_f32 v[80:81], v[64:65], v[80:81]
	v_lshlrev_b32_e32 v64, 16, v165
	v_and_b32_e32 v65, 0xffff0000, v165
	s_mov_b64 s[8:9], 0x30100
	v_pk_mul_f32 v[72:73], v[76:77], v[76:77]
	v_pk_mul_f32 v[76:77], v[84:85], v[84:85]
	v_pk_add_f32 v[84:85], v[66:67], v[64:65]
	v_lshl_add_u64 v[82:83], v[212:213], 0, s[8:9]
	v_cvt_pk_bf16_f32 v64, v68, v69
	v_cvt_pk_bf16_f32 v65, v70, v71
	v_cvt_pk_bf16_f32 v66, v80, v81
	v_cvt_pk_bf16_f32 v67, v84, v85
	global_store_dwordx4 v[82:83], v[64:67], off sc1
	v_pk_mul_f32 v[74:75], v[78:79], v[78:79]
	v_pk_mul_f32 v[78:79], v[86:87], v[86:87]
	v_pk_mul_f32 v[64:65], v[68:69], v[68:69]
	v_pk_mul_f32 v[66:67], v[70:71], v[70:71]
	v_add_f32_e32 v64, v64, v65
	v_add_f32_e32 v66, v66, v67
	v_pk_mul_f32 v[68:69], v[80:81], v[80:81]
	v_pk_mul_f32 v[70:71], v[84:85], v[84:85]
	v_add_f32_e32 v64, v64, v66
	v_add_f32_e32 v65, v78, v79
	v_add_f32_e32 v66, v76, v77
	v_add_f32_e32 v70, v70, v71
	v_add_f32_e32 v68, v68, v69
	v_add_f32_e32 v65, v66, v65
	v_add_f32_e32 v66, v74, v75
	v_add_f32_e32 v67, v72, v73
	v_add_f32_e32 v68, v68, v70
	v_add_f32_e32 v66, v67, v66
	v_add_f32_e32 v64, v64, v68
	v_add_f32_e32 v65, v66, v65
	v_add_f32_e32 v64, v65, v64
	ds_bpermute_b32 v65, v226, v64
	s_waitcnt lgkmcnt(0)
	v_add_f32_e32 v64, v64, v65
	ds_bpermute_b32 v65, v227, v64
	s_and_saveexec_b64 s[8:9], s[40:41]
	s_cbranch_execz .LBB0_1395
	s_waitcnt lgkmcnt(0)
	v_add_f32_e32 v64, v64, v65
	v_mul_f32_e32 v64, 0x4b800000, v64
	v_trunc_f32_e32 v64, v64
	v_mul_f32_e32 v65, 0x2f800000, v64
	v_floor_f32_e32 v65, v65
	v_fmac_f32_e32 v64, 0xcf800000, v65
	v_cvt_u32_f32_e32 v64, v64
	v_cvt_u32_f32_e32 v65, v65
	v_lshl_add_u64 v[66:67], v[210:211], 3, s[46:47]
	global_atomic_add_x2 v[66:67], v[64:65], off offset:384
.LBB0_1395:
	s_or_b64 exec, exec, s[8:9]
	v_lshlrev_b32_e32 v68, 16, v154
	v_and_b32_e32 v69, 0xffff0000, v154
	v_pk_add_f32 v[60:61], v[60:61], v[68:69]
	v_lshlrev_b32_e32 v68, 16, v155
	v_and_b32_e32 v69, 0xffff0000, v155
	v_pk_add_f32 v[62:63], v[62:63], v[68:69]
	v_lshlrev_b32_e32 v68, 16, v156
	v_and_b32_e32 v69, 0xffff0000, v156
	v_pk_add_f32 v[68:69], v[56:57], v[68:69]
	v_lshlrev_b32_e32 v56, 16, v157
	v_and_b32_e32 v57, 0xffff0000, v157
	s_mov_b64 s[8:9], 0x80000
	v_pk_add_f32 v[70:71], v[58:59], v[56:57]
	s_waitcnt lgkmcnt(0)
	v_lshl_add_u64 v[64:65], v[212:213], 0, s[8:9]
	v_cvt_pk_bf16_f32 v56, v60, v61
	v_cvt_pk_bf16_f32 v57, v62, v63
	v_cvt_pk_bf16_f32 v58, v68, v69
	v_cvt_pk_bf16_f32 v59, v70, v71
	global_store_dwordx4 v[64:65], v[56:59], off sc1
	v_lshlrev_b32_e32 v64, 16, v146
	v_and_b32_e32 v65, 0xffff0000, v146
	v_pk_add_f32 v[52:53], v[52:53], v[64:65]
	v_lshlrev_b32_e32 v64, 16, v147
	v_and_b32_e32 v65, 0xffff0000, v147
	v_pk_add_f32 v[54:55], v[54:55], v[64:65]
	v_lshlrev_b32_e32 v64, 16, v148
	v_and_b32_e32 v65, 0xffff0000, v148
	v_pk_add_f32 v[64:65], v[48:49], v[64:65]
	v_lshlrev_b32_e32 v48, 16, v149
	v_and_b32_e32 v49, 0xffff0000, v149
	s_mov_b64 s[8:9], 0x80100
	v_pk_mul_f32 v[56:57], v[60:61], v[60:61]
	v_pk_mul_f32 v[60:61], v[68:69], v[68:69]
	v_pk_add_f32 v[68:69], v[50:51], v[48:49]
	v_lshl_add_u64 v[66:67], v[212:213], 0, s[8:9]
	v_cvt_pk_bf16_f32 v48, v52, v53
	v_cvt_pk_bf16_f32 v49, v54, v55
	v_cvt_pk_bf16_f32 v50, v64, v65
	v_cvt_pk_bf16_f32 v51, v68, v69
	global_store_dwordx4 v[66:67], v[48:51], off sc1
	v_pk_mul_f32 v[58:59], v[62:63], v[62:63]
	v_pk_mul_f32 v[62:63], v[70:71], v[70:71]
	v_pk_mul_f32 v[48:49], v[52:53], v[52:53]
	v_pk_mul_f32 v[50:51], v[54:55], v[54:55]
	v_add_f32_e32 v48, v48, v49
	v_add_f32_e32 v50, v50, v51
	v_pk_mul_f32 v[52:53], v[64:65], v[64:65]
	v_pk_mul_f32 v[54:55], v[68:69], v[68:69]
	v_add_f32_e32 v48, v48, v50
	v_add_f32_e32 v49, v62, v63
	v_add_f32_e32 v50, v60, v61
	v_add_f32_e32 v54, v54, v55
	v_add_f32_e32 v52, v52, v53
	v_add_f32_e32 v49, v50, v49
	v_add_f32_e32 v50, v58, v59
	v_add_f32_e32 v51, v56, v57
	v_add_f32_e32 v52, v52, v54
	v_add_f32_e32 v50, v51, v50
	v_add_f32_e32 v48, v48, v52
	v_add_f32_e32 v49, v50, v49
	v_add_f32_e32 v48, v49, v48
	ds_bpermute_b32 v49, v226, v48
	s_waitcnt lgkmcnt(0)
	v_add_f32_e32 v48, v48, v49
	ds_bpermute_b32 v49, v227, v48
	s_and_saveexec_b64 s[8:9], s[40:41]
	s_cbranch_execz .LBB0_1397
	s_waitcnt lgkmcnt(0)
	v_add_f32_e32 v48, v48, v49
	v_mul_f32_e32 v48, 0x4b800000, v48
	v_trunc_f32_e32 v48, v48
	v_mul_f32_e32 v49, 0x2f800000, v48
	v_floor_f32_e32 v49, v49
	v_fmac_f32_e32 v48, 0xcf800000, v49
	v_cvt_u32_f32_e32 v48, v48
	v_cvt_u32_f32_e32 v49, v49
	v_lshl_add_u64 v[50:51], v[210:211], 3, s[46:47]
	global_atomic_add_x2 v[50:51], v[48:49], off offset:1024
.LBB0_1397:
	s_or_b64 exec, exec, s[8:9]
	v_lshlrev_b32_e32 v52, 16, v138
	v_and_b32_e32 v53, 0xffff0000, v138
	v_pk_add_f32 v[44:45], v[44:45], v[52:53]
	v_lshlrev_b32_e32 v52, 16, v139
	v_and_b32_e32 v53, 0xffff0000, v139
	v_pk_add_f32 v[46:47], v[46:47], v[52:53]
	v_lshlrev_b32_e32 v52, 16, v140
	v_and_b32_e32 v53, 0xffff0000, v140
	v_pk_add_f32 v[52:53], v[40:41], v[52:53]
	v_lshlrev_b32_e32 v40, 16, v141
	v_and_b32_e32 v41, 0xffff0000, v141
	s_mov_b64 s[8:9], 0x90000
	v_pk_add_f32 v[54:55], v[42:43], v[40:41]
	s_waitcnt lgkmcnt(0)
	v_lshl_add_u64 v[48:49], v[212:213], 0, s[8:9]
	v_cvt_pk_bf16_f32 v40, v44, v45
	v_cvt_pk_bf16_f32 v41, v46, v47
	v_cvt_pk_bf16_f32 v42, v52, v53
	v_cvt_pk_bf16_f32 v43, v54, v55
	global_store_dwordx4 v[48:49], v[40:43], off sc1
	v_lshlrev_b32_e32 v48, 16, v130
	v_and_b32_e32 v49, 0xffff0000, v130
	v_pk_add_f32 v[36:37], v[36:37], v[48:49]
	v_lshlrev_b32_e32 v48, 16, v131
	v_and_b32_e32 v49, 0xffff0000, v131
	v_pk_add_f32 v[38:39], v[38:39], v[48:49]
	v_lshlrev_b32_e32 v48, 16, v132
	v_and_b32_e32 v49, 0xffff0000, v132
	v_pk_add_f32 v[48:49], v[32:33], v[48:49]
	v_lshlrev_b32_e32 v32, 16, v133
	v_and_b32_e32 v33, 0xffff0000, v133
	s_mov_b64 s[8:9], 0x90100
	v_pk_mul_f32 v[40:41], v[44:45], v[44:45]
	v_pk_mul_f32 v[44:45], v[52:53], v[52:53]
	v_pk_add_f32 v[52:53], v[34:35], v[32:33]
	v_lshl_add_u64 v[50:51], v[212:213], 0, s[8:9]
	v_cvt_pk_bf16_f32 v32, v36, v37
	v_cvt_pk_bf16_f32 v33, v38, v39
	v_cvt_pk_bf16_f32 v34, v48, v49
	v_cvt_pk_bf16_f32 v35, v52, v53
	global_store_dwordx4 v[50:51], v[32:35], off sc1
	v_pk_mul_f32 v[42:43], v[46:47], v[46:47]
	v_pk_mul_f32 v[46:47], v[54:55], v[54:55]
	v_pk_mul_f32 v[32:33], v[36:37], v[36:37]
	v_pk_mul_f32 v[34:35], v[38:39], v[38:39]
	v_add_f32_e32 v32, v32, v33
	v_add_f32_e32 v34, v34, v35
	v_pk_mul_f32 v[36:37], v[48:49], v[48:49]
	v_pk_mul_f32 v[38:39], v[52:53], v[52:53]
	v_add_f32_e32 v32, v32, v34
	v_add_f32_e32 v33, v46, v47
	v_add_f32_e32 v34, v44, v45
	v_add_f32_e32 v38, v38, v39
	v_add_f32_e32 v36, v36, v37
	v_add_f32_e32 v33, v34, v33
	v_add_f32_e32 v34, v42, v43
	v_add_f32_e32 v35, v40, v41
	v_add_f32_e32 v36, v36, v38
	v_add_f32_e32 v34, v35, v34
	v_add_f32_e32 v32, v32, v36
	v_add_f32_e32 v33, v34, v33
	v_add_f32_e32 v32, v33, v32
	ds_bpermute_b32 v33, v226, v32
	s_waitcnt lgkmcnt(0)
	v_add_f32_e32 v32, v32, v33
	ds_bpermute_b32 v33, v227, v32
	s_and_saveexec_b64 s[8:9], s[40:41]
	s_cbranch_execz .LBB0_1399
	s_waitcnt lgkmcnt(0)
	v_add_f32_e32 v32, v32, v33
	v_mul_f32_e32 v32, 0x4b800000, v32
	v_trunc_f32_e32 v32, v32
	v_mul_f32_e32 v33, 0x2f800000, v32
	v_floor_f32_e32 v33, v33
	v_fmac_f32_e32 v32, 0xcf800000, v33
	v_cvt_u32_f32_e32 v32, v32
	v_cvt_u32_f32_e32 v33, v33
	v_lshl_add_u64 v[34:35], v[210:211], 3, s[46:47]
	global_atomic_add_x2 v[34:35], v[32:33], off offset:1152
.LBB0_1399:
	s_or_b64 exec, exec, s[8:9]
	v_lshlrev_b32_e32 v36, 16, v116
	v_and_b32_e32 v37, 0xffff0000, v116
	v_pk_add_f32 v[28:29], v[28:29], v[36:37]
	v_lshlrev_b32_e32 v36, 16, v117
	v_and_b32_e32 v37, 0xffff0000, v117
	v_pk_add_f32 v[30:31], v[30:31], v[36:37]
	v_lshlrev_b32_e32 v36, 16, v118
	v_and_b32_e32 v37, 0xffff0000, v118
	v_pk_add_f32 v[36:37], v[24:25], v[36:37]
	v_lshlrev_b32_e32 v24, 16, v119
	v_and_b32_e32 v25, 0xffff0000, v119
	s_mov_b64 s[8:9], 0xa0000
	v_pk_add_f32 v[38:39], v[26:27], v[24:25]
	s_waitcnt lgkmcnt(0)
	v_lshl_add_u64 v[32:33], v[212:213], 0, s[8:9]
	v_cvt_pk_bf16_f32 v24, v28, v29
	v_cvt_pk_bf16_f32 v25, v30, v31
	v_cvt_pk_bf16_f32 v26, v36, v37
	v_cvt_pk_bf16_f32 v27, v38, v39
	global_store_dwordx4 v[32:33], v[24:27], off sc1
	v_lshlrev_b32_e32 v32, 16, v104
	v_and_b32_e32 v33, 0xffff0000, v104
	v_pk_add_f32 v[20:21], v[20:21], v[32:33]
	v_lshlrev_b32_e32 v32, 16, v105
	v_and_b32_e32 v33, 0xffff0000, v105
	v_pk_add_f32 v[22:23], v[22:23], v[32:33]
	v_lshlrev_b32_e32 v32, 16, v106
	v_and_b32_e32 v33, 0xffff0000, v106
	v_pk_add_f32 v[32:33], v[16:17], v[32:33]
	v_lshlrev_b32_e32 v16, 16, v107
	v_and_b32_e32 v17, 0xffff0000, v107
	s_mov_b64 s[8:9], 0xa0100
	v_pk_mul_f32 v[24:25], v[28:29], v[28:29]
	v_pk_mul_f32 v[28:29], v[36:37], v[36:37]
	v_pk_add_f32 v[36:37], v[18:19], v[16:17]
	v_lshl_add_u64 v[34:35], v[212:213], 0, s[8:9]
	v_cvt_pk_bf16_f32 v16, v20, v21
	v_cvt_pk_bf16_f32 v17, v22, v23
	v_cvt_pk_bf16_f32 v18, v32, v33
	v_cvt_pk_bf16_f32 v19, v36, v37
	global_store_dwordx4 v[34:35], v[16:19], off sc1
	v_pk_mul_f32 v[26:27], v[30:31], v[30:31]
	v_pk_mul_f32 v[30:31], v[38:39], v[38:39]
	v_pk_mul_f32 v[16:17], v[20:21], v[20:21]
	v_pk_mul_f32 v[18:19], v[22:23], v[22:23]
	v_add_f32_e32 v16, v16, v17
	v_add_f32_e32 v18, v18, v19
	v_pk_mul_f32 v[20:21], v[32:33], v[32:33]
	v_pk_mul_f32 v[22:23], v[36:37], v[36:37]
	v_add_f32_e32 v16, v16, v18
	v_add_f32_e32 v17, v30, v31
	v_add_f32_e32 v18, v28, v29
	v_add_f32_e32 v22, v22, v23
	v_add_f32_e32 v20, v20, v21
	v_add_f32_e32 v17, v18, v17
	v_add_f32_e32 v18, v26, v27
	v_add_f32_e32 v19, v24, v25
	v_add_f32_e32 v20, v20, v22
	v_add_f32_e32 v18, v19, v18
	v_add_f32_e32 v16, v16, v20
	v_add_f32_e32 v17, v18, v17
	v_add_f32_e32 v16, v17, v16
	ds_bpermute_b32 v17, v226, v16
	s_waitcnt lgkmcnt(0)
	v_add_f32_e32 v16, v16, v17
	ds_bpermute_b32 v17, v227, v16
	s_and_saveexec_b64 s[8:9], s[40:41]
	s_cbranch_execz .LBB0_1401
	s_waitcnt lgkmcnt(0)
	v_add_f32_e32 v16, v16, v17
	v_mul_f32_e32 v16, 0x4b800000, v16
	v_trunc_f32_e32 v16, v16
	v_mul_f32_e32 v17, 0x2f800000, v16
	v_floor_f32_e32 v17, v17
	v_fmac_f32_e32 v16, 0xcf800000, v17
	v_cvt_u32_f32_e32 v16, v16
	v_cvt_u32_f32_e32 v17, v17
	v_lshl_add_u64 v[18:19], v[210:211], 3, s[46:47]
	global_atomic_add_x2 v[18:19], v[16:17], off offset:1280
.LBB0_1401:
	s_or_b64 exec, exec, s[8:9]
	v_lshlrev_b32_e32 v20, 16, v92
	v_and_b32_e32 v21, 0xffff0000, v92
	v_pk_add_f32 v[12:13], v[12:13], v[20:21]
	v_lshlrev_b32_e32 v20, 16, v93
	v_and_b32_e32 v21, 0xffff0000, v93
	v_pk_add_f32 v[14:15], v[14:15], v[20:21]
	v_lshlrev_b32_e32 v20, 16, v94
	v_and_b32_e32 v21, 0xffff0000, v94
	v_pk_add_f32 v[20:21], v[8:9], v[20:21]
	v_lshlrev_b32_e32 v8, 16, v95
	v_and_b32_e32 v9, 0xffff0000, v95
	s_mov_b64 s[8:9], 0xb0000
	v_pk_add_f32 v[22:23], v[10:11], v[8:9]
	s_waitcnt lgkmcnt(0)
	v_lshl_add_u64 v[16:17], v[212:213], 0, s[8:9]
	v_cvt_pk_bf16_f32 v8, v12, v13
	v_cvt_pk_bf16_f32 v9, v14, v15
	v_cvt_pk_bf16_f32 v10, v20, v21
	v_cvt_pk_bf16_f32 v11, v22, v23
	global_store_dwordx4 v[16:17], v[8:11], off sc1
	v_lshlrev_b32_e32 v16, 16, v88
	v_and_b32_e32 v17, 0xffff0000, v88
	v_pk_add_f32 v[4:5], v[4:5], v[16:17]
	v_lshlrev_b32_e32 v16, 16, v89
	v_and_b32_e32 v17, 0xffff0000, v89
	v_pk_add_f32 v[6:7], v[6:7], v[16:17]
	v_lshlrev_b32_e32 v16, 16, v90
	v_and_b32_e32 v17, 0xffff0000, v90
	v_pk_add_f32 v[16:17], v[0:1], v[16:17]
	v_lshlrev_b32_e32 v0, 16, v91
	v_and_b32_e32 v1, 0xffff0000, v91
	s_mov_b64 s[8:9], 0xb0100
	v_pk_mul_f32 v[8:9], v[12:13], v[12:13]
	v_pk_mul_f32 v[12:13], v[20:21], v[20:21]
	v_pk_add_f32 v[20:21], v[2:3], v[0:1]
	v_lshl_add_u64 v[18:19], v[212:213], 0, s[8:9]
	v_cvt_pk_bf16_f32 v0, v4, v5
	v_cvt_pk_bf16_f32 v1, v6, v7
	v_cvt_pk_bf16_f32 v2, v16, v17
	v_cvt_pk_bf16_f32 v3, v20, v21
	global_store_dwordx4 v[18:19], v[0:3], off sc1
	v_pk_mul_f32 v[10:11], v[14:15], v[14:15]
	v_pk_mul_f32 v[14:15], v[22:23], v[22:23]
	v_pk_mul_f32 v[0:1], v[4:5], v[4:5]
	v_pk_mul_f32 v[2:3], v[6:7], v[6:7]
	v_add_f32_e32 v0, v0, v1
	v_add_f32_e32 v2, v2, v3
	v_pk_mul_f32 v[4:5], v[16:17], v[16:17]
	v_pk_mul_f32 v[6:7], v[20:21], v[20:21]
	v_add_f32_e32 v0, v0, v2
	v_add_f32_e32 v1, v14, v15
	v_add_f32_e32 v2, v12, v13
	v_add_f32_e32 v6, v6, v7
	v_add_f32_e32 v4, v4, v5
	v_add_f32_e32 v1, v2, v1
	v_add_f32_e32 v2, v10, v11
	v_add_f32_e32 v3, v8, v9
	v_add_f32_e32 v4, v4, v6
	v_add_f32_e32 v2, v3, v2
	v_add_f32_e32 v0, v0, v4
	v_add_f32_e32 v1, v2, v1
	v_add_f32_e32 v0, v1, v0
	ds_bpermute_b32 v1, v226, v0
	s_waitcnt lgkmcnt(0)
	v_add_f32_e32 v0, v0, v1
	ds_bpermute_b32 v1, v227, v0
	s_and_saveexec_b64 s[8:9], s[40:41]
	s_cbranch_execz .LBB0_1403
	s_waitcnt lgkmcnt(0)
	v_add_f32_e32 v0, v0, v1
	v_mul_f32_e32 v0, 0x4b800000, v0
	v_trunc_f32_e32 v0, v0
	v_mul_f32_e32 v1, 0x2f800000, v0
	v_floor_f32_e32 v1, v1
	v_fmac_f32_e32 v0, 0xcf800000, v1
	v_cvt_u32_f32_e32 v0, v0
	v_cvt_u32_f32_e32 v1, v1
	v_lshl_add_u64 v[2:3], v[210:211], 3, s[46:47]
	global_atomic_add_x2 v[2:3], v[0:1], off offset:1408

.LBB0_1621:
	v_lshl_add_u32 v210, s74, 8, v222
	v_ashrrev_i32_e32 v211, 31, v210
	v_lshl_or_b32 v88, s73, 8, v224
	v_lshlrev_b64 v[90:91], 12, v[210:211]
	v_lshl_add_u64 v[90:91], s[30:31], 0, v[90:91]
	v_ashrrev_i32_e32 v89, 31, v88
	v_lshl_add_u64 v[212:213], v[88:89], 1, v[90:91]
	global_load_dwordx4 v[228:231], v[212:213], off
	global_load_dwordx4 v[186:189], v[212:213], off offset:256
	v_add_co_u32_e32 v88, vcc, 0x10000, v212
	v_readlane_b32 s8, v237, 51
	s_nop 0
	v_addc_co_u32_e32 v89, vcc, 0, v213, vcc
	v_readlane_b32 s11, v237, 54
	global_load_dwordx4 v[182:185], v[88:89], off
	global_load_dwordx4 v[178:181], v[88:89], off offset:256
	v_add_co_u32_e32 v88, vcc, s11, v212
	s_mov_b32 s8, 0x80000
	s_nop 0
	v_addc_co_u32_e32 v89, vcc, 0, v213, vcc
	global_load_dwordx4 v[174:177], v[88:89], off
	global_load_dwordx4 v[170:173], v[88:89], off offset:256
	v_add_co_u32_e32 v88, vcc, 0x30000, v212
	v_and_b32_e32 v227, 64, v214
	s_nop 0
	v_addc_co_u32_e32 v89, vcc, 0, v213, vcc
	global_load_dwordx4 v[166:169], v[88:89], off
	global_load_dwordx4 v[162:165], v[88:89], off offset:256
	v_add_co_u32_e32 v88, vcc, s8, v212
	s_mov_b32 s8, 0xb0000
	s_nop 0
	v_addc_co_u32_e32 v89, vcc, 0, v213, vcc
	global_load_dwordx4 v[154:157], v[88:89], off
	global_load_dwordx4 v[146:149], v[88:89], off offset:256
	v_add_co_u32_e32 v88, vcc, 0x90000, v212
	v_xor_b32_e32 v226, 16, v214
	s_nop 0
	v_addc_co_u32_e32 v89, vcc, 0, v213, vcc
	global_load_dwordx4 v[134:137], v[88:89], off
	global_load_dwordx4 v[130:133], v[88:89], off offset:256
	v_add_co_u32_e32 v88, vcc, 0xa0000, v212
	v_add_u32_e32 v227, 64, v227
	s_nop 0
	v_addc_co_u32_e32 v89, vcc, 0, v213, vcc
	global_load_dwordx4 v[116:119], v[88:89], off
	global_load_dwordx4 v[104:107], v[88:89], off offset:256
	v_add_co_u32_e32 v88, vcc, s8, v212
	v_xor_b32_e32 v232, 32, v214
	s_nop 0
	v_addc_co_u32_e32 v89, vcc, 0, v213, vcc
	global_load_dwordx4 v[92:95], v[88:89], off
	s_nop 0
	global_load_dwordx4 v[88:91], v[88:89], off offset:256
	v_cmp_lt_i32_e32 vcc, v226, v227
	v_readlane_b32 s9, v237, 52
	v_readlane_b32 s10, v237, 53
	v_cndmask_b32_e32 v226, v214, v226, vcc
	v_cmp_lt_i32_e32 vcc, v232, v227
	v_lshlrev_b32_e32 v226, 2, v226
	s_waitcnt vmcnt(0)
	v_and_b32_e32 v233, 0xffff0000, v228
	v_cndmask_b32_e32 v227, v214, v232, vcc
	v_lshlrev_b32_e32 v232, 16, v228
	v_lshlrev_b32_e32 v228, 16, v229
	v_and_b32_e32 v229, 0xffff0000, v229
	v_pk_add_f32 v[160:161], v[160:161], v[228:229]
	v_lshlrev_b32_e32 v228, 16, v230
	v_and_b32_e32 v229, 0xffff0000, v230
	v_pk_add_f32 v[228:229], v[150:151], v[228:229]
	v_lshlrev_b32_e32 v150, 16, v231
	v_and_b32_e32 v151, 0xffff0000, v231
	v_pk_add_f32 v[158:159], v[158:159], v[232:233]
	v_pk_add_f32 v[230:231], v[152:153], v[150:151]
	v_cvt_pk_bf16_f32 v150, v158, v159
	v_cvt_pk_bf16_f32 v151, v160, v161
	v_cvt_pk_bf16_f32 v152, v228, v229
	v_cvt_pk_bf16_f32 v153, v230, v231
	global_store_dwordx4 v[212:213], v[150:153], off sc1
	v_lshlrev_b32_e32 v227, 2, v227
	s_nop 0
	v_pk_mul_f32 v[150:151], v[158:159], v[158:159]
	v_pk_mul_f32 v[158:159], v[228:229], v[228:229]
	v_lshlrev_b32_e32 v228, 16, v186
	v_and_b32_e32 v229, 0xffff0000, v186
	v_lshlrev_b32_e32 v186, 16, v187
	v_and_b32_e32 v187, 0xffff0000, v187
	v_pk_add_f32 v[144:145], v[144:145], v[186:187]
	v_lshlrev_b32_e32 v186, 16, v188
	v_and_b32_e32 v187, 0xffff0000, v188
	v_pk_add_f32 v[186:187], v[138:139], v[186:187]
	v_lshlrev_b32_e32 v138, 16, v189
	v_and_b32_e32 v139, 0xffff0000, v189
	v_pk_add_f32 v[142:143], v[142:143], v[228:229]
	v_pk_add_f32 v[188:189], v[140:141], v[138:139]
	v_cvt_pk_bf16_f32 v138, v142, v143
	v_cvt_pk_bf16_f32 v139, v144, v145
	v_cvt_pk_bf16_f32 v140, v186, v187
	v_cvt_pk_bf16_f32 v141, v188, v189
	global_store_dwordx4 v[212:213], v[138:141], off offset:256 sc1
	v_pk_mul_f32 v[152:153], v[160:161], v[160:161]
	v_pk_mul_f32 v[160:161], v[230:231], v[230:231]
	v_pk_mul_f32 v[138:139], v[142:143], v[142:143]
	v_pk_mul_f32 v[140:141], v[144:145], v[144:145]
	v_add_f32_e32 v138, v138, v139
	v_add_f32_e32 v140, v140, v141
	v_pk_mul_f32 v[142:143], v[186:187], v[186:187]
	v_pk_mul_f32 v[144:145], v[188:189], v[188:189]
	v_add_f32_e32 v138, v138, v140
	v_add_f32_e32 v139, v160, v161
	v_add_f32_e32 v140, v158, v159
	v_add_f32_e32 v144, v144, v145
	v_add_f32_e32 v142, v142, v143
	v_add_f32_e32 v139, v140, v139
	v_add_f32_e32 v140, v152, v153
	v_add_f32_e32 v141, v150, v151
	v_add_f32_e32 v142, v142, v144
	v_add_f32_e32 v140, v141, v140
	v_add_f32_e32 v138, v138, v142
	v_add_f32_e32 v139, v140, v139
	v_add_f32_e32 v138, v139, v138
	ds_bpermute_b32 v139, v226, v138
	s_waitcnt lgkmcnt(0)
	v_add_f32_e32 v138, v138, v139
	ds_bpermute_b32 v139, v227, v138
	s_and_saveexec_b64 s[8:9], s[38:39]
	s_cbranch_execz .LBB0_1623
	s_waitcnt lgkmcnt(0)
	v_add_f32_e32 v138, v138, v139
	v_mul_f32_e32 v138, 0x4b800000, v138
	v_trunc_f32_e32 v138, v138
	v_mul_f32_e32 v139, 0x2f800000, v138
	v_floor_f32_e32 v139, v139
	v_fmac_f32_e32 v138, 0xcf800000, v139
	v_cvt_u32_f32_e32 v138, v138
	v_cvt_u32_f32_e32 v139, v139
	v_lshl_add_u64 v[140:141], v[210:211], 3, s[44:45]
	global_atomic_add_x2 v[140:141], v[138:139], off
.LBB0_1623:
	s_or_b64 exec, exec, s[8:9]
	v_lshlrev_b32_e32 v142, 16, v182
	v_and_b32_e32 v143, 0xffff0000, v182
	v_pk_add_f32 v[124:125], v[124:125], v[142:143]
	v_lshlrev_b32_e32 v142, 16, v183
	v_and_b32_e32 v143, 0xffff0000, v183
	v_pk_add_f32 v[126:127], v[126:127], v[142:143]
	v_lshlrev_b32_e32 v142, 16, v184
	v_and_b32_e32 v143, 0xffff0000, v184
	v_pk_add_f32 v[142:143], v[120:121], v[142:143]
	v_lshlrev_b32_e32 v120, 16, v185
	v_and_b32_e32 v121, 0xffff0000, v185
	s_mov_b64 s[8:9], 0x10000
	v_pk_add_f32 v[144:145], v[122:123], v[120:121]
	s_waitcnt lgkmcnt(0)
	v_lshl_add_u64 v[138:139], v[212:213], 0, s[8:9]
	v_cvt_pk_bf16_f32 v120, v124, v125
	v_cvt_pk_bf16_f32 v121, v126, v127
	v_cvt_pk_bf16_f32 v122, v142, v143
	v_cvt_pk_bf16_f32 v123, v144, v145
	global_store_dwordx4 v[138:139], v[120:123], off sc1
	v_lshlrev_b32_e32 v138, 16, v178
	v_and_b32_e32 v139, 0xffff0000, v178
	v_pk_add_f32 v[112:113], v[112:113], v[138:139]
	v_lshlrev_b32_e32 v138, 16, v179
	v_and_b32_e32 v139, 0xffff0000, v179
	v_pk_add_f32 v[114:115], v[114:115], v[138:139]
	v_lshlrev_b32_e32 v138, 16, v180
	v_and_b32_e32 v139, 0xffff0000, v180
	v_pk_add_f32 v[138:139], v[108:109], v[138:139]
	v_lshlrev_b32_e32 v108, 16, v181
	v_and_b32_e32 v109, 0xffff0000, v181
	s_mov_b64 s[8:9], 0x10100
	v_pk_mul_f32 v[120:121], v[124:125], v[124:125]
	v_pk_mul_f32 v[124:125], v[142:143], v[142:143]
	v_pk_add_f32 v[142:143], v[110:111], v[108:109]
	v_lshl_add_u64 v[140:141], v[212:213], 0, s[8:9]
	v_cvt_pk_bf16_f32 v108, v112, v113
	v_cvt_pk_bf16_f32 v109, v114, v115
	v_cvt_pk_bf16_f32 v110, v138, v139
	v_cvt_pk_bf16_f32 v111, v142, v143
	global_store_dwordx4 v[140:141], v[108:111], off sc1
	v_pk_mul_f32 v[122:123], v[126:127], v[126:127]
	v_pk_mul_f32 v[126:127], v[144:145], v[144:145]
	v_pk_mul_f32 v[108:109], v[112:113], v[112:113]
	v_pk_mul_f32 v[110:111], v[114:115], v[114:115]
	v_add_f32_e32 v108, v108, v109
	v_add_f32_e32 v110, v110, v111
	v_pk_mul_f32 v[112:113], v[138:139], v[138:139]
	v_pk_mul_f32 v[114:115], v[142:143], v[142:143]
	v_add_f32_e32 v108, v108, v110
	v_add_f32_e32 v109, v126, v127
	v_add_f32_e32 v110, v124, v125
	v_add_f32_e32 v114, v114, v115
	v_add_f32_e32 v112, v112, v113
	v_add_f32_e32 v109, v110, v109
	v_add_f32_e32 v110, v122, v123
	v_add_f32_e32 v111, v120, v121
	v_add_f32_e32 v112, v112, v114
	v_add_f32_e32 v110, v111, v110
	v_add_f32_e32 v108, v108, v112
	v_add_f32_e32 v109, v110, v109
	v_add_f32_e32 v108, v109, v108
	ds_bpermute_b32 v109, v226, v108
	s_waitcnt lgkmcnt(0)
	v_add_f32_e32 v108, v108, v109
	ds_bpermute_b32 v109, v227, v108
	s_and_saveexec_b64 s[8:9], s[38:39]
	s_cbranch_execz .LBB0_1625
	s_waitcnt lgkmcnt(0)
	v_add_f32_e32 v108, v108, v109
	v_mul_f32_e32 v108, 0x4b800000, v108
	v_trunc_f32_e32 v108, v108
	v_mul_f32_e32 v109, 0x2f800000, v108
	v_floor_f32_e32 v109, v109
	v_fmac_f32_e32 v108, 0xcf800000, v109
	v_cvt_u32_f32_e32 v108, v108
	v_cvt_u32_f32_e32 v109, v109
	v_lshl_add_u64 v[110:111], v[210:211], 3, s[44:45]
	global_atomic_add_x2 v[110:111], v[108:109], off offset:128
.LBB0_1625:
	s_or_b64 exec, exec, s[8:9]
	v_lshlrev_b32_e32 v112, 16, v174
	v_and_b32_e32 v113, 0xffff0000, v174
	v_pk_add_f32 v[100:101], v[100:101], v[112:113]
	v_lshlrev_b32_e32 v112, 16, v175
	v_and_b32_e32 v113, 0xffff0000, v175
	v_pk_add_f32 v[102:103], v[102:103], v[112:113]
	v_lshlrev_b32_e32 v112, 16, v176
	v_and_b32_e32 v113, 0xffff0000, v176
	v_pk_add_f32 v[112:113], v[96:97], v[112:113]
	v_lshlrev_b32_e32 v96, 16, v177
	v_and_b32_e32 v97, 0xffff0000, v177
	s_mov_b64 s[8:9], 0x20000
	v_pk_add_f32 v[114:115], v[98:99], v[96:97]
	s_waitcnt lgkmcnt(0)
	v_lshl_add_u64 v[108:109], v[212:213], 0, s[8:9]
	v_cvt_pk_bf16_f32 v96, v100, v101
	v_cvt_pk_bf16_f32 v97, v102, v103
	v_cvt_pk_bf16_f32 v98, v112, v113
	v_cvt_pk_bf16_f32 v99, v114, v115
	global_store_dwordx4 v[108:109], v[96:99], off sc1
	v_lshlrev_b32_e32 v108, 16, v170
	v_and_b32_e32 v109, 0xffff0000, v170
	v_pk_add_f32 v[84:85], v[84:85], v[108:109]
	v_lshlrev_b32_e32 v108, 16, v171
	v_and_b32_e32 v109, 0xffff0000, v171
	v_pk_add_f32 v[86:87], v[86:87], v[108:109]
	v_lshlrev_b32_e32 v108, 16, v172
	v_and_b32_e32 v109, 0xffff0000, v172
	v_pk_add_f32 v[108:109], v[80:81], v[108:109]
	v_lshlrev_b32_e32 v80, 16, v173
	v_and_b32_e32 v81, 0xffff0000, v173
	s_mov_b64 s[8:9], 0x20100
	v_pk_mul_f32 v[96:97], v[100:101], v[100:101]
	v_pk_mul_f32 v[100:101], v[112:113], v[112:113]
	v_pk_add_f32 v[112:113], v[82:83], v[80:81]
	v_lshl_add_u64 v[110:111], v[212:213], 0, s[8:9]
	v_cvt_pk_bf16_f32 v80, v84, v85
	v_cvt_pk_bf16_f32 v81, v86, v87
	v_cvt_pk_bf16_f32 v82, v108, v109
	v_cvt_pk_bf16_f32 v83, v112, v113
	global_store_dwordx4 v[110:111], v[80:83], off sc1
	v_pk_mul_f32 v[98:99], v[102:103], v[102:103]
	v_pk_mul_f32 v[102:103], v[114:115], v[114:115]
	v_pk_mul_f32 v[80:81], v[84:85], v[84:85]
	v_pk_mul_f32 v[82:83], v[86:87], v[86:87]
	v_add_f32_e32 v80, v80, v81
	v_add_f32_e32 v82, v82, v83
	v_pk_mul_f32 v[84:85], v[108:109], v[108:109]
	v_pk_mul_f32 v[86:87], v[112:113], v[112:113]
	v_add_f32_e32 v80, v80, v82
	v_add_f32_e32 v81, v102, v103
	v_add_f32_e32 v82, v100, v101
	v_add_f32_e32 v86, v86, v87
	v_add_f32_e32 v84, v84, v85
	v_add_f32_e32 v81, v82, v81
	v_add_f32_e32 v82, v98, v99
	v_add_f32_e32 v83, v96, v97
	v_add_f32_e32 v84, v84, v86
	v_add_f32_e32 v82, v83, v82
	v_add_f32_e32 v80, v80, v84
	v_add_f32_e32 v81, v82, v81
	v_add_f32_e32 v80, v81, v80
	ds_bpermute_b32 v81, v226, v80
	s_waitcnt lgkmcnt(0)
	v_add_f32_e32 v80, v80, v81
	ds_bpermute_b32 v81, v227, v80
	s_and_saveexec_b64 s[8:9], s[38:39]
	s_cbranch_execz .LBB0_1627
	s_waitcnt lgkmcnt(0)
	v_add_f32_e32 v80, v80, v81
	v_mul_f32_e32 v80, 0x4b800000, v80
	v_trunc_f32_e32 v80, v80
	v_mul_f32_e32 v81, 0x2f800000, v80
	v_floor_f32_e32 v81, v81
	v_fmac_f32_e32 v80, 0xcf800000, v81
	v_cvt_u32_f32_e32 v80, v80
	v_cvt_u32_f32_e32 v81, v81
	v_lshl_add_u64 v[82:83], v[210:211], 3, s[44:45]
	global_atomic_add_x2 v[82:83], v[80:81], off offset:256
.LBB0_1627:
	s_or_b64 exec, exec, s[8:9]
	v_lshlrev_b32_e32 v84, 16, v166
	v_and_b32_e32 v85, 0xffff0000, v166
	v_pk_add_f32 v[76:77], v[76:77], v[84:85]
	v_lshlrev_b32_e32 v84, 16, v167
	v_and_b32_e32 v85, 0xffff0000, v167
	v_pk_add_f32 v[78:79], v[78:79], v[84:85]
	v_lshlrev_b32_e32 v84, 16, v168
	v_and_b32_e32 v85, 0xffff0000, v168
	v_pk_add_f32 v[84:85], v[72:73], v[84:85]
	v_lshlrev_b32_e32 v72, 16, v169
	v_and_b32_e32 v73, 0xffff0000, v169
	s_mov_b64 s[8:9], 0x30000
	v_pk_add_f32 v[86:87], v[74:75], v[72:73]
	s_waitcnt lgkmcnt(0)
	v_lshl_add_u64 v[80:81], v[212:213], 0, s[8:9]
	v_cvt_pk_bf16_f32 v72, v76, v77
	v_cvt_pk_bf16_f32 v73, v78, v79
	v_cvt_pk_bf16_f32 v74, v84, v85
	v_cvt_pk_bf16_f32 v75, v86, v87
	global_store_dwordx4 v[80:81], v[72:75], off sc1
	v_lshlrev_b32_e32 v80, 16, v162
	v_and_b32_e32 v81, 0xffff0000, v162
	v_pk_add_f32 v[68:69], v[68:69], v[80:81]
	v_lshlrev_b32_e32 v80, 16, v163
	v_and_b32_e32 v81, 0xffff0000, v163
	v_pk_add_f32 v[70:71], v[70:71], v[80:81]
	v_lshlrev_b32_e32 v80, 16, v164
	v_and_b32_e32 v81, 0xffff0000, v164
	v_pk_add_f32 v[80:81], v[64:65], v[80:81]
	v_lshlrev_b32_e32 v64, 16, v165
	v_and_b32_e32 v65, 0xffff0000, v165
	s_mov_b64 s[8:9], 0x30100
	v_pk_mul_f32 v[72:73], v[76:77], v[76:77]
	v_pk_mul_f32 v[76:77], v[84:85], v[84:85]
	v_pk_add_f32 v[84:85], v[66:67], v[64:65]
	v_lshl_add_u64 v[82:83], v[212:213], 0, s[8:9]
	v_cvt_pk_bf16_f32 v64, v68, v69
	v_cvt_pk_bf16_f32 v65, v70, v71
	v_cvt_pk_bf16_f32 v66, v80, v81
	v_cvt_pk_bf16_f32 v67, v84, v85
	global_store_dwordx4 v[82:83], v[64:67], off sc1
	v_pk_mul_f32 v[74:75], v[78:79], v[78:79]
	v_pk_mul_f32 v[78:79], v[86:87], v[86:87]
	v_pk_mul_f32 v[64:65], v[68:69], v[68:69]
	v_pk_mul_f32 v[66:67], v[70:71], v[70:71]
	v_add_f32_e32 v64, v64, v65
	v_add_f32_e32 v66, v66, v67
	v_pk_mul_f32 v[68:69], v[80:81], v[80:81]
	v_pk_mul_f32 v[70:71], v[84:85], v[84:85]
	v_add_f32_e32 v64, v64, v66
	v_add_f32_e32 v65, v78, v79
	v_add_f32_e32 v66, v76, v77
	v_add_f32_e32 v70, v70, v71
	v_add_f32_e32 v68, v68, v69
	v_add_f32_e32 v65, v66, v65
	v_add_f32_e32 v66, v74, v75
	v_add_f32_e32 v67, v72, v73
	v_add_f32_e32 v68, v68, v70
	v_add_f32_e32 v66, v67, v66
	v_add_f32_e32 v64, v64, v68
	v_add_f32_e32 v65, v66, v65
	v_add_f32_e32 v64, v65, v64
	ds_bpermute_b32 v65, v226, v64
	s_waitcnt lgkmcnt(0)
	v_add_f32_e32 v64, v64, v65
	ds_bpermute_b32 v65, v227, v64
	s_and_saveexec_b64 s[8:9], s[38:39]
	s_cbranch_execz .LBB0_1629
	s_waitcnt lgkmcnt(0)
	v_add_f32_e32 v64, v64, v65
	v_mul_f32_e32 v64, 0x4b800000, v64
	v_trunc_f32_e32 v64, v64
	v_mul_f32_e32 v65, 0x2f800000, v64
	v_floor_f32_e32 v65, v65
	v_fmac_f32_e32 v64, 0xcf800000, v65
	v_cvt_u32_f32_e32 v64, v64
	v_cvt_u32_f32_e32 v65, v65
	v_lshl_add_u64 v[66:67], v[210:211], 3, s[44:45]
	global_atomic_add_x2 v[66:67], v[64:65], off offset:384
.LBB0_1629:
	s_or_b64 exec, exec, s[8:9]
	v_lshlrev_b32_e32 v68, 16, v154
	v_and_b32_e32 v69, 0xffff0000, v154
	v_pk_add_f32 v[60:61], v[60:61], v[68:69]
	v_lshlrev_b32_e32 v68, 16, v155
	v_and_b32_e32 v69, 0xffff0000, v155
	v_pk_add_f32 v[62:63], v[62:63], v[68:69]
	v_lshlrev_b32_e32 v68, 16, v156
	v_and_b32_e32 v69, 0xffff0000, v156
	v_pk_add_f32 v[68:69], v[56:57], v[68:69]
	v_lshlrev_b32_e32 v56, 16, v157
	v_and_b32_e32 v57, 0xffff0000, v157
	s_mov_b64 s[8:9], 0x80000
	v_pk_add_f32 v[70:71], v[58:59], v[56:57]
	s_waitcnt lgkmcnt(0)
	v_lshl_add_u64 v[64:65], v[212:213], 0, s[8:9]
	v_cvt_pk_bf16_f32 v56, v60, v61
	v_cvt_pk_bf16_f32 v57, v62, v63
	v_cvt_pk_bf16_f32 v58, v68, v69
	v_cvt_pk_bf16_f32 v59, v70, v71
	global_store_dwordx4 v[64:65], v[56:59], off sc1
	v_lshlrev_b32_e32 v64, 16, v146
	v_and_b32_e32 v65, 0xffff0000, v146
	v_pk_add_f32 v[52:53], v[52:53], v[64:65]
	v_lshlrev_b32_e32 v64, 16, v147
	v_and_b32_e32 v65, 0xffff0000, v147
	v_pk_add_f32 v[54:55], v[54:55], v[64:65]
	v_lshlrev_b32_e32 v64, 16, v148
	v_and_b32_e32 v65, 0xffff0000, v148
	v_pk_add_f32 v[64:65], v[48:49], v[64:65]
	v_lshlrev_b32_e32 v48, 16, v149
	v_and_b32_e32 v49, 0xffff0000, v149
	s_mov_b64 s[8:9], 0x80100
	v_pk_mul_f32 v[56:57], v[60:61], v[60:61]
	v_pk_mul_f32 v[60:61], v[68:69], v[68:69]
	v_pk_add_f32 v[68:69], v[50:51], v[48:49]
	v_lshl_add_u64 v[66:67], v[212:213], 0, s[8:9]
	v_cvt_pk_bf16_f32 v48, v52, v53
	v_cvt_pk_bf16_f32 v49, v54, v55
	v_cvt_pk_bf16_f32 v50, v64, v65
	v_cvt_pk_bf16_f32 v51, v68, v69
	global_store_dwordx4 v[66:67], v[48:51], off sc1
	v_pk_mul_f32 v[58:59], v[62:63], v[62:63]
	v_pk_mul_f32 v[62:63], v[70:71], v[70:71]
	v_pk_mul_f32 v[48:49], v[52:53], v[52:53]
	v_pk_mul_f32 v[50:51], v[54:55], v[54:55]
	v_add_f32_e32 v48, v48, v49
	v_add_f32_e32 v50, v50, v51
	v_pk_mul_f32 v[52:53], v[64:65], v[64:65]
	v_pk_mul_f32 v[54:55], v[68:69], v[68:69]
	v_add_f32_e32 v48, v48, v50
	v_add_f32_e32 v49, v62, v63
	v_add_f32_e32 v50, v60, v61
	v_add_f32_e32 v54, v54, v55
	v_add_f32_e32 v52, v52, v53
	v_add_f32_e32 v49, v50, v49
	v_add_f32_e32 v50, v58, v59
	v_add_f32_e32 v51, v56, v57
	v_add_f32_e32 v52, v52, v54
	v_add_f32_e32 v50, v51, v50
	v_add_f32_e32 v48, v48, v52
	v_add_f32_e32 v49, v50, v49
	v_add_f32_e32 v48, v49, v48
	ds_bpermute_b32 v49, v226, v48
	s_waitcnt lgkmcnt(0)
	v_add_f32_e32 v48, v48, v49
	ds_bpermute_b32 v49, v227, v48
	s_and_saveexec_b64 s[8:9], s[38:39]
	s_cbranch_execz .LBB0_1631
	s_waitcnt lgkmcnt(0)
	v_add_f32_e32 v48, v48, v49
	v_mul_f32_e32 v48, 0x4b800000, v48
	v_trunc_f32_e32 v48, v48
	v_mul_f32_e32 v49, 0x2f800000, v48
	v_floor_f32_e32 v49, v49
	v_fmac_f32_e32 v48, 0xcf800000, v49
	v_cvt_u32_f32_e32 v48, v48
	v_cvt_u32_f32_e32 v49, v49
	v_lshl_add_u64 v[50:51], v[210:211], 3, s[44:45]
	global_atomic_add_x2 v[50:51], v[48:49], off offset:1024
.LBB0_1631:
	s_or_b64 exec, exec, s[8:9]
	v_lshlrev_b32_e32 v52, 16, v134
	v_and_b32_e32 v53, 0xffff0000, v134
	v_pk_add_f32 v[44:45], v[44:45], v[52:53]
	v_lshlrev_b32_e32 v52, 16, v135
	v_and_b32_e32 v53, 0xffff0000, v135
	v_pk_add_f32 v[46:47], v[46:47], v[52:53]
	v_lshlrev_b32_e32 v52, 16, v136
	v_and_b32_e32 v53, 0xffff0000, v136
	v_pk_add_f32 v[52:53], v[40:41], v[52:53]
	v_lshlrev_b32_e32 v40, 16, v137
	v_and_b32_e32 v41, 0xffff0000, v137
	s_mov_b64 s[8:9], 0x90000
	v_pk_add_f32 v[54:55], v[42:43], v[40:41]
	s_waitcnt lgkmcnt(0)
	v_lshl_add_u64 v[48:49], v[212:213], 0, s[8:9]
	v_cvt_pk_bf16_f32 v40, v44, v45
	v_cvt_pk_bf16_f32 v41, v46, v47
	v_cvt_pk_bf16_f32 v42, v52, v53
	v_cvt_pk_bf16_f32 v43, v54, v55
	global_store_dwordx4 v[48:49], v[40:43], off sc1
	v_lshlrev_b32_e32 v48, 16, v130
	v_and_b32_e32 v49, 0xffff0000, v130
	v_pk_add_f32 v[36:37], v[36:37], v[48:49]
	v_lshlrev_b32_e32 v48, 16, v131
	v_and_b32_e32 v49, 0xffff0000, v131
	v_pk_add_f32 v[38:39], v[38:39], v[48:49]
	v_lshlrev_b32_e32 v48, 16, v132
	v_and_b32_e32 v49, 0xffff0000, v132
	v_pk_add_f32 v[48:49], v[32:33], v[48:49]
	v_lshlrev_b32_e32 v32, 16, v133
	v_and_b32_e32 v33, 0xffff0000, v133
	s_mov_b64 s[8:9], 0x90100
	v_pk_mul_f32 v[40:41], v[44:45], v[44:45]
	v_pk_mul_f32 v[44:45], v[52:53], v[52:53]
	v_pk_add_f32 v[52:53], v[34:35], v[32:33]
	v_lshl_add_u64 v[50:51], v[212:213], 0, s[8:9]
	v_cvt_pk_bf16_f32 v32, v36, v37
	v_cvt_pk_bf16_f32 v33, v38, v39
	v_cvt_pk_bf16_f32 v34, v48, v49
	v_cvt_pk_bf16_f32 v35, v52, v53
	global_store_dwordx4 v[50:51], v[32:35], off sc1
	v_pk_mul_f32 v[42:43], v[46:47], v[46:47]
	v_pk_mul_f32 v[46:47], v[54:55], v[54:55]
	v_pk_mul_f32 v[32:33], v[36:37], v[36:37]
	v_pk_mul_f32 v[34:35], v[38:39], v[38:39]
	v_add_f32_e32 v32, v32, v33
	v_add_f32_e32 v34, v34, v35
	v_pk_mul_f32 v[36:37], v[48:49], v[48:49]
	v_pk_mul_f32 v[38:39], v[52:53], v[52:53]
	v_add_f32_e32 v32, v32, v34
	v_add_f32_e32 v33, v46, v47
	v_add_f32_e32 v34, v44, v45
	v_add_f32_e32 v38, v38, v39
	v_add_f32_e32 v36, v36, v37
	v_add_f32_e32 v33, v34, v33
	v_add_f32_e32 v34, v42, v43
	v_add_f32_e32 v35, v40, v41
	v_add_f32_e32 v36, v36, v38
	v_add_f32_e32 v34, v35, v34
	v_add_f32_e32 v32, v32, v36
	v_add_f32_e32 v33, v34, v33
	v_add_f32_e32 v32, v33, v32
	ds_bpermute_b32 v33, v226, v32
	s_waitcnt lgkmcnt(0)
	v_add_f32_e32 v32, v32, v33
	ds_bpermute_b32 v33, v227, v32
	s_and_saveexec_b64 s[8:9], s[38:39]
	s_cbranch_execz .LBB0_1633
	s_waitcnt lgkmcnt(0)
	v_add_f32_e32 v32, v32, v33
	v_mul_f32_e32 v32, 0x4b800000, v32
	v_trunc_f32_e32 v32, v32
	v_mul_f32_e32 v33, 0x2f800000, v32
	v_floor_f32_e32 v33, v33
	v_fmac_f32_e32 v32, 0xcf800000, v33
	v_cvt_u32_f32_e32 v32, v32
	v_cvt_u32_f32_e32 v33, v33
	v_lshl_add_u64 v[34:35], v[210:211], 3, s[44:45]
	global_atomic_add_x2 v[34:35], v[32:33], off offset:1152
.LBB0_1633:
	s_or_b64 exec, exec, s[8:9]
	v_lshlrev_b32_e32 v36, 16, v116
	v_and_b32_e32 v37, 0xffff0000, v116
	v_pk_add_f32 v[28:29], v[28:29], v[36:37]
	v_lshlrev_b32_e32 v36, 16, v117
	v_and_b32_e32 v37, 0xffff0000, v117
	v_pk_add_f32 v[30:31], v[30:31], v[36:37]
	v_lshlrev_b32_e32 v36, 16, v118
	v_and_b32_e32 v37, 0xffff0000, v118
	v_pk_add_f32 v[36:37], v[24:25], v[36:37]
	v_lshlrev_b32_e32 v24, 16, v119
	v_and_b32_e32 v25, 0xffff0000, v119
	s_mov_b64 s[8:9], 0xa0000
	v_pk_add_f32 v[38:39], v[26:27], v[24:25]
	s_waitcnt lgkmcnt(0)
	v_lshl_add_u64 v[32:33], v[212:213], 0, s[8:9]
	v_cvt_pk_bf16_f32 v24, v28, v29
	v_cvt_pk_bf16_f32 v25, v30, v31
	v_cvt_pk_bf16_f32 v26, v36, v37
	v_cvt_pk_bf16_f32 v27, v38, v39
	global_store_dwordx4 v[32:33], v[24:27], off sc1
	v_lshlrev_b32_e32 v32, 16, v104
	v_and_b32_e32 v33, 0xffff0000, v104
	v_pk_add_f32 v[20:21], v[20:21], v[32:33]
	v_lshlrev_b32_e32 v32, 16, v105
	v_and_b32_e32 v33, 0xffff0000, v105
	v_pk_add_f32 v[22:23], v[22:23], v[32:33]
	v_lshlrev_b32_e32 v32, 16, v106
	v_and_b32_e32 v33, 0xffff0000, v106
	v_pk_add_f32 v[32:33], v[16:17], v[32:33]
	v_lshlrev_b32_e32 v16, 16, v107
	v_and_b32_e32 v17, 0xffff0000, v107
	s_mov_b64 s[8:9], 0xa0100
	v_pk_mul_f32 v[24:25], v[28:29], v[28:29]
	v_pk_mul_f32 v[28:29], v[36:37], v[36:37]
	v_pk_add_f32 v[36:37], v[18:19], v[16:17]
	v_lshl_add_u64 v[34:35], v[212:213], 0, s[8:9]
	v_cvt_pk_bf16_f32 v16, v20, v21
	v_cvt_pk_bf16_f32 v17, v22, v23
	v_cvt_pk_bf16_f32 v18, v32, v33
	v_cvt_pk_bf16_f32 v19, v36, v37
	global_store_dwordx4 v[34:35], v[16:19], off sc1
	v_pk_mul_f32 v[26:27], v[30:31], v[30:31]
	v_pk_mul_f32 v[30:31], v[38:39], v[38:39]
	v_pk_mul_f32 v[16:17], v[20:21], v[20:21]
	v_pk_mul_f32 v[18:19], v[22:23], v[22:23]
	v_add_f32_e32 v16, v16, v17
	v_add_f32_e32 v18, v18, v19
	v_pk_mul_f32 v[20:21], v[32:33], v[32:33]
	v_pk_mul_f32 v[22:23], v[36:37], v[36:37]
	v_add_f32_e32 v16, v16, v18
	v_add_f32_e32 v17, v30, v31
	v_add_f32_e32 v18, v28, v29
	v_add_f32_e32 v22, v22, v23
	v_add_f32_e32 v20, v20, v21
	v_add_f32_e32 v17, v18, v17
	v_add_f32_e32 v18, v26, v27
	v_add_f32_e32 v19, v24, v25
	v_add_f32_e32 v20, v20, v22
	v_add_f32_e32 v18, v19, v18
	v_add_f32_e32 v16, v16, v20
	v_add_f32_e32 v17, v18, v17
	v_add_f32_e32 v16, v17, v16
	ds_bpermute_b32 v17, v226, v16
	s_waitcnt lgkmcnt(0)
	v_add_f32_e32 v16, v16, v17
	ds_bpermute_b32 v17, v227, v16
	s_and_saveexec_b64 s[8:9], s[38:39]
	s_cbranch_execz .LBB0_1635
	s_waitcnt lgkmcnt(0)
	v_add_f32_e32 v16, v16, v17
	v_mul_f32_e32 v16, 0x4b800000, v16
	v_trunc_f32_e32 v16, v16
	v_mul_f32_e32 v17, 0x2f800000, v16
	v_floor_f32_e32 v17, v17
	v_fmac_f32_e32 v16, 0xcf800000, v17
	v_cvt_u32_f32_e32 v16, v16
	v_cvt_u32_f32_e32 v17, v17
	v_lshl_add_u64 v[18:19], v[210:211], 3, s[44:45]
	global_atomic_add_x2 v[18:19], v[16:17], off offset:1280
.LBB0_1635:
	s_or_b64 exec, exec, s[8:9]
	v_lshlrev_b32_e32 v20, 16, v92
	v_and_b32_e32 v21, 0xffff0000, v92
	v_pk_add_f32 v[12:13], v[12:13], v[20:21]
	v_lshlrev_b32_e32 v20, 16, v93
	v_and_b32_e32 v21, 0xffff0000, v93
	v_pk_add_f32 v[14:15], v[14:15], v[20:21]
	v_lshlrev_b32_e32 v20, 16, v94
	v_and_b32_e32 v21, 0xffff0000, v94
	v_pk_add_f32 v[20:21], v[8:9], v[20:21]
	v_lshlrev_b32_e32 v8, 16, v95
	v_and_b32_e32 v9, 0xffff0000, v95
	s_mov_b64 s[8:9], 0xb0000
	v_pk_add_f32 v[22:23], v[10:11], v[8:9]
	s_waitcnt lgkmcnt(0)
	v_lshl_add_u64 v[16:17], v[212:213], 0, s[8:9]
	v_cvt_pk_bf16_f32 v8, v12, v13
	v_cvt_pk_bf16_f32 v9, v14, v15
	v_cvt_pk_bf16_f32 v10, v20, v21
	v_cvt_pk_bf16_f32 v11, v22, v23
	global_store_dwordx4 v[16:17], v[8:11], off sc1
	v_lshlrev_b32_e32 v16, 16, v88
	v_and_b32_e32 v17, 0xffff0000, v88
	v_pk_add_f32 v[4:5], v[4:5], v[16:17]
	v_lshlrev_b32_e32 v16, 16, v89
	v_and_b32_e32 v17, 0xffff0000, v89
	v_pk_add_f32 v[6:7], v[6:7], v[16:17]
	v_lshlrev_b32_e32 v16, 16, v90
	v_and_b32_e32 v17, 0xffff0000, v90
	v_pk_add_f32 v[16:17], v[0:1], v[16:17]
	v_lshlrev_b32_e32 v0, 16, v91
	v_and_b32_e32 v1, 0xffff0000, v91
	s_mov_b64 s[8:9], 0xb0100
	v_pk_mul_f32 v[8:9], v[12:13], v[12:13]
	v_pk_mul_f32 v[12:13], v[20:21], v[20:21]
	v_pk_add_f32 v[20:21], v[2:3], v[0:1]
	v_lshl_add_u64 v[18:19], v[212:213], 0, s[8:9]
	v_cvt_pk_bf16_f32 v0, v4, v5
	v_cvt_pk_bf16_f32 v1, v6, v7
	v_cvt_pk_bf16_f32 v2, v16, v17
	v_cvt_pk_bf16_f32 v3, v20, v21
	global_store_dwordx4 v[18:19], v[0:3], off sc1
	v_pk_mul_f32 v[10:11], v[14:15], v[14:15]
	v_pk_mul_f32 v[14:15], v[22:23], v[22:23]
	v_pk_mul_f32 v[0:1], v[4:5], v[4:5]
	v_pk_mul_f32 v[2:3], v[6:7], v[6:7]
	v_add_f32_e32 v0, v0, v1
	v_add_f32_e32 v2, v2, v3
	v_pk_mul_f32 v[4:5], v[16:17], v[16:17]
	v_pk_mul_f32 v[6:7], v[20:21], v[20:21]
	v_add_f32_e32 v0, v0, v2
	v_add_f32_e32 v1, v14, v15
	v_add_f32_e32 v2, v12, v13
	v_add_f32_e32 v6, v6, v7
	v_add_f32_e32 v4, v4, v5
	v_add_f32_e32 v1, v2, v1
	v_add_f32_e32 v2, v10, v11
	v_add_f32_e32 v3, v8, v9
	v_add_f32_e32 v4, v4, v6
	v_add_f32_e32 v2, v3, v2
	v_add_f32_e32 v0, v0, v4
	v_add_f32_e32 v1, v2, v1
	v_add_f32_e32 v0, v1, v0
	ds_bpermute_b32 v1, v226, v0
	s_waitcnt lgkmcnt(0)
	v_add_f32_e32 v0, v0, v1
	ds_bpermute_b32 v1, v227, v0
	s_and_saveexec_b64 s[8:9], s[38:39]
	s_cbranch_execz .LBB0_1637
	s_waitcnt lgkmcnt(0)
	v_add_f32_e32 v0, v0, v1
	v_mul_f32_e32 v0, 0x4b800000, v0
	v_trunc_f32_e32 v0, v0
	v_mul_f32_e32 v1, 0x2f800000, v0
	v_floor_f32_e32 v1, v1
	v_fmac_f32_e32 v0, 0xcf800000, v1
	v_cvt_u32_f32_e32 v0, v0
	v_cvt_u32_f32_e32 v1, v1
	v_lshl_add_u64 v[2:3], v[210:211], 3, s[44:45]
	global_atomic_add_x2 v[2:3], v[0:1], off offset:1408
